# v15 plus swiglu epilogue: second half row-scale loads hoisted ahead of first half stores (counted vmcnt)
# speedup vs baseline: 1.0051x; 1.0051x over previous
; #define PG8_STAGE(bufoff, gbase, voff) do { _Pragma("unroll") for (int _i = 0; _i < 2; ++_i) \
;     __builtin_amdgcn_global_load_lds((const unsigned*)((const char*)(gbase) + (voff)[_i]), (PG8_LAS unsigned*)(lds + (bufoff) + ldsw + _i * 8192), 16, 0, 0); } while (0)
; #define PG8_LDA(dst, b, h) do { _Pragma("unroll") for (int m = 0; m < 4; ++m) _Pragma("unroll") for (int k = 0; k < 2; ++k) dst[m][k] = *(const PG8_LAS bf16x8*)(lds + PG8_SA(b, h) + aoff + m * 2048 + k * 1024); } while (0)
; #define PG8_LDB(dst, b, h) do { _Pragma("unroll") for (int n = 0; n < 2; ++n) _Pragma("unroll") for (int k = 0; k < 2; ++k) dst[n][k] = *(const PG8_LAS bf16x8*)(lds + PG8_SB(b, h) + boff + n * 2048 + k * 1024); } while (0)
; #define PG8_BAR __builtin_amdgcn_s_barrier()
; template <class Epi>
; DI void gemm_phase(PG8_LAS unsigned char* lds, const Gemm g, const StaticOrder& S, const Epi& E, const int wv) {
;     ...
;     for (int t = 0; t < nt; t += 2) {
;       const bool last = (t == nt - 2);
;       const char* a1 = cA + (size_t)(t + 1) * kstep;
;       const char* a2 = last ? nA : cA + (size_t)(t + 2) * kstep; const char* b2 = last ? nB : cB + (size_t)(t + 2) * kstep;
;       const char* a3 = a2 + kstep; const char* b3 = b2 + kstep;
;       PG8_LDB(B0, 0, 0); PG8_SCHED; PG8_LDA(At, 0, 0); PG8_STAGE(PG8_SA(1, 1), a1 + hstep, voffA);
;       PG8_WAIT_L(8); PG8_BAR; PG8_WAIT_L(0); PG8_MMA(0, 0, At, B0); PG8_BAR; PG8_SCHED;
;       PG8_LDB(B1, 0, 1); PG8_STAGE(PG8_SB(0, 0), b2, voffB);
;       PG8_BAR; PG8_WAIT_L(0); PG8_MMA(0, 1, At, B1); PG8_BAR;
;       PG8_LDA(At, 0, 1); PG8_STAGE(PG8_SA(0, 0), a2, voffA);
;       PG8_BAR; PG8_WAIT_L(0); PG8_MMA(1, 0, At, B0); PG8_BAR; PG8_SCHED;
;       PG8_STAGE(PG8_SB(0, 1), b2 + hstep, voffB);
;       PG8_WAIT_V(6); PG8_BAR; PG8_MMA(1, 1, At, B1); PG8_BAR;
;       PG8_LDB(B0, 1, 0); PG8_SCHED; PG8_LDA(At, 1, 0); PG8_STAGE(PG8_SA(0, 1), a2 + hstep, voffA);
;       PG8_WAIT_L(8); PG8_BAR; PG8_WAIT_L(0); PG8_MMA(0, 0, At, B0); PG8_BAR; PG8_SCHED;
;       PG8_LDB(B1, 1, 1); PG8_STAGE(PG8_SB(1, 0), b3, voffB);
;       PG8_BAR; PG8_WAIT_L(0); PG8_MMA(0, 1, At, B1); PG8_BAR;
;       PG8_LDA(At, 1, 1); PG8_STAGE(PG8_SA(1, 0), a3, voffA);
;       PG8_BAR; PG8_WAIT_L(0); PG8_MMA(1, 0, At, B0); PG8_BAR; PG8_SCHED;
;       PG8_STAGE(PG8_SB(1, 1), b3 + hstep, voffB);
;       PG8_WAIT_V(6); PG8_BAR; PG8_MMA(1, 1, At, B1); PG8_BAR;
;     }
.LBB0_893:
	ds_read_b128 v[142:145], v155
	ds_read_b128 v[146:149], v155 offset:1024
	ds_read_b128 v[160:163], v155 offset:2048
	ds_read_b128 v[164:167], v155 offset:3072
	s_add_u32 s8, s6, 0xfffc0080
	s_addc_u32 s9, s7, -1
	s_cmp_eq_u32 s62, 12
	s_cselect_b32 s37, s5, s9
	s_cselect_b32 s36, s27, s8
	s_cselect_b32 s9, s25, s61
	s_cselect_b32 s8, s59, s60
	v_lshl_add_u64 v[150:151], s[6:7], 0, v[136:137]
	s_add_i32 m0, s35, 0xc000
	ds_read_b128 v[168:171], v156
	ds_read_b128 v[172:175], v156 offset:1024
	ds_read_b128 v[176:179], v156 offset:2048
	ds_read_b128 v[180:183], v156 offset:3072
	ds_read_b128 v[184:187], v156 offset:4096
	ds_read_b128 v[188:191], v156 offset:5120
	ds_read_b128 v[192:195], v156 offset:6144
	ds_read_b128 v[196:199], v156 offset:7168
	global_load_lds_dwordx4 v[150:151], off
	v_lshl_add_u64 v[150:151], s[6:7], 0, v[138:139]
	s_add_i32 m0, s35, 0xe000
	s_nop 0
	global_load_lds_dwordx4 v[150:151], off
	s_waitcnt lgkmcnt(8)
	s_barrier
	s_waitcnt lgkmcnt(0)
	s_setprio 1
	s_waitcnt lgkmcnt(0)
	v_mfma_f32_16x16x32_bf16 v[116:119], v[142:145], v[168:171], v[116:119]
	v_mfma_f32_16x16x32_bf16 v[112:115], v[160:163], v[168:171], v[112:115]
	v_mfma_f32_16x16x32_bf16 v[108:111], v[142:145], v[176:179], v[108:111]
	v_mfma_f32_16x16x32_bf16 v[100:103], v[160:163], v[176:179], v[100:103]
	v_mfma_f32_16x16x32_bf16 v[92:95], v[142:145], v[184:187], v[92:95]
	v_mfma_f32_16x16x32_bf16 v[84:87], v[160:163], v[184:187], v[84:87]
	v_mfma_f32_16x16x32_bf16 v[76:79], v[142:145], v[192:195], v[76:79]
	v_mfma_f32_16x16x32_bf16 v[68:71], v[160:163], v[192:195], v[68:71]
	v_mfma_f32_16x16x32_bf16 v[116:119], v[146:149], v[172:175], v[116:119]
	v_mfma_f32_16x16x32_bf16 v[112:115], v[164:167], v[172:175], v[112:115]
	v_mfma_f32_16x16x32_bf16 v[108:111], v[146:149], v[180:183], v[108:111]
	v_mfma_f32_16x16x32_bf16 v[100:103], v[164:167], v[180:183], v[100:103]
	v_mfma_f32_16x16x32_bf16 v[92:95], v[146:149], v[188:191], v[92:95]
	v_mfma_f32_16x16x32_bf16 v[84:87], v[164:167], v[188:191], v[84:87]
	v_mfma_f32_16x16x32_bf16 v[76:79], v[146:149], v[196:199], v[76:79]
	v_mfma_f32_16x16x32_bf16 v[68:71], v[164:167], v[196:199], v[68:71]
	s_setprio 0
	s_barrier
	s_add_i32 s63, s54, s45
	v_lshl_add_u64 v[150:151], s[8:9], 0, v[130:131]
	s_mov_b32 m0, s63
	ds_read_b128 v[200:203], v157
	ds_read_b128 v[204:207], v157 offset:1024
	ds_read_b128 v[208:211], v157 offset:2048
	ds_read_b128 v[212:215], v157 offset:3072
	global_load_lds_dwordx4 v[150:151], off
	v_lshl_add_u64 v[216:217], s[8:9], 0, v[134:135]
	s_add_i32 m0, s63, 0x2000
	s_nop 0
	global_load_lds_dwordx4 v[216:217], off
	s_barrier
	s_waitcnt lgkmcnt(0)
	s_setprio 1
	s_waitcnt lgkmcnt(0)
	v_mfma_f32_16x16x32_bf16 v[124:127], v[200:203], v[168:171], v[124:127]
	v_mfma_f32_16x16x32_bf16 v[120:123], v[208:211], v[168:171], v[120:123]
	v_mfma_f32_16x16x32_bf16 v[104:107], v[200:203], v[176:179], v[104:107]
	v_mfma_f32_16x16x32_bf16 v[96:99], v[208:211], v[176:179], v[96:99]
	v_mfma_f32_16x16x32_bf16 v[88:91], v[200:203], v[184:187], v[88:91]
	v_mfma_f32_16x16x32_bf16 v[80:83], v[208:211], v[184:187], v[80:83]
	v_mfma_f32_16x16x32_bf16 v[72:75], v[200:203], v[192:195], v[72:75]
	v_mfma_f32_16x16x32_bf16 v[64:67], v[208:211], v[192:195], v[64:67]
	v_mfma_f32_16x16x32_bf16 v[124:127], v[204:207], v[172:175], v[124:127]
	v_mfma_f32_16x16x32_bf16 v[120:123], v[212:215], v[172:175], v[120:123]
	v_mfma_f32_16x16x32_bf16 v[104:107], v[204:207], v[180:183], v[104:107]
	v_mfma_f32_16x16x32_bf16 v[96:99], v[212:215], v[180:183], v[96:99]
	v_mfma_f32_16x16x32_bf16 v[88:91], v[204:207], v[188:191], v[88:91]
	v_mfma_f32_16x16x32_bf16 v[80:83], v[212:215], v[188:191], v[80:83]
	v_mfma_f32_16x16x32_bf16 v[72:75], v[204:207], v[196:199], v[72:75]
	v_mfma_f32_16x16x32_bf16 v[64:67], v[212:215], v[196:199], v[64:67]
	s_setprio 0
	s_mov_b32 m0, s35
	v_lshl_add_u64 v[220:221], s[36:37], 0, v[128:129]
	s_barrier
	ds_read_b128 v[168:171], v156 offset:16384
	ds_read_b128 v[172:175], v156 offset:17408
	ds_read_b128 v[176:179], v156 offset:18432
	ds_read_b128 v[180:183], v156 offset:19456
	ds_read_b128 v[184:187], v156 offset:20480
	ds_read_b128 v[188:191], v156 offset:21504
	ds_read_b128 v[192:195], v156 offset:22528
	ds_read_b128 v[196:199], v156 offset:23552
	global_load_lds_dwordx4 v[220:221], off
	v_lshl_add_u64 v[222:223], s[36:37], 0, v[132:133]
	s_mov_b32 m0, s46
	s_nop 0
	global_load_lds_dwordx4 v[222:223], off
	s_barrier
	s_waitcnt lgkmcnt(0)
	s_setprio 1
	s_waitcnt lgkmcnt(0)
	v_mfma_f32_16x16x32_bf16 v[52:55], v[142:145], v[168:171], v[52:55]
	v_mfma_f32_16x16x32_bf16 v[48:51], v[160:163], v[168:171], v[48:51]
	v_mfma_f32_16x16x32_bf16 v[44:47], v[142:145], v[176:179], v[44:47]
	v_mfma_f32_16x16x32_bf16 v[36:39], v[160:163], v[176:179], v[36:39]
	v_mfma_f32_16x16x32_bf16 v[28:31], v[142:145], v[184:187], v[28:31]
	v_mfma_f32_16x16x32_bf16 v[20:23], v[160:163], v[184:187], v[20:23]
	v_mfma_f32_16x16x32_bf16 v[12:15], v[142:145], v[192:195], v[12:15]
	v_mfma_f32_16x16x32_bf16 v[4:7], v[160:163], v[192:195], v[4:7]
	v_mfma_f32_16x16x32_bf16 v[52:55], v[146:149], v[172:175], v[52:55]
	v_mfma_f32_16x16x32_bf16 v[48:51], v[164:167], v[172:175], v[48:51]
	v_mfma_f32_16x16x32_bf16 v[44:47], v[146:149], v[180:183], v[44:47]
	v_mfma_f32_16x16x32_bf16 v[36:39], v[164:167], v[180:183], v[36:39]
	v_mfma_f32_16x16x32_bf16 v[28:31], v[146:149], v[188:191], v[28:31]
	v_mfma_f32_16x16x32_bf16 v[20:23], v[164:167], v[188:191], v[20:23]
	v_mfma_f32_16x16x32_bf16 v[12:15], v[146:149], v[196:199], v[12:15]
	v_mfma_f32_16x16x32_bf16 v[4:7], v[164:167], v[196:199], v[4:7]
	s_setprio 0
	s_barrier
; #define PG8_STAGE(bufoff, gbase, voff) do { _Pragma("unroll") for (int _i = 0; _i < 2; ++_i) \
;     __builtin_amdgcn_global_load_lds((const unsigned*)((const char*)(gbase) + (voff)[_i]), (PG8_LAS unsigned*)(lds + (bufoff) + ldsw + _i * 8192), 16, 0, 0); } while (0)
; #define PG8_LDA(dst, b, h) do { _Pragma("unroll") for (int m = 0; m < 4; ++m) _Pragma("unroll") for (int k = 0; k < 2; ++k) dst[m][k] = *(const PG8_LAS bf16x8*)(lds + PG8_SA(b, h) + aoff + m * 2048 + k * 1024); } while (0)
; #define PG8_LDB(dst, b, h) do { _Pragma("unroll") for (int n = 0; n < 2; ++n) _Pragma("unroll") for (int k = 0; k < 2; ++k) dst[n][k] = *(const PG8_LAS bf16x8*)(lds + PG8_SB(b, h) + boff + n * 2048 + k * 1024); } while (0)
; #define PG8_MMA(ai, bj, At, Bt) do { __builtin_amdgcn_s_setprio(1); _Pragma("unroll") for (int m = 0; m < 4; ++m) _Pragma("unroll") for (int n = 0; n < 2; ++n) _Pragma("unroll") for (int k = 0; k < 2; ++k) \
;     acc[ai][bj][m][n] = __builtin_amdgcn_mfma_f32_16x16x32_bf16(Bt[n][k], At[m][k], acc[ai][bj][m][n], 0, 0, 0); __builtin_amdgcn_s_setprio(0); } while (0)
; #define PG8_WAIT_V(n) asm volatile("s_waitcnt vmcnt(" #n ")" ::: "memory")
; #define PG8_WAIT_L(n) asm volatile("s_waitcnt lgkmcnt(" #n ")" ::: "memory")
; #define PG8_BAR __builtin_amdgcn_s_barrier()
; #define PG8_SCHED __builtin_amdgcn_sched_barrier(0)
; template <class Epi>
; DI void gemm_phase(PG8_LAS unsigned char* lds, const Gemm g, const StaticOrder& S, const Epi& E, const int wv) {
;     ...
;       PG8_LDA(At, 0, 1); PG8_STAGE(PG8_SA(0, 0), a2, voffA);
;       PG8_BAR; PG8_WAIT_L(0); PG8_MMA(1, 0, At, B0); PG8_BAR; PG8_SCHED;
;       PG8_STAGE(PG8_SB(0, 1), b2 + hstep, voffB);
;       PG8_WAIT_V(6); PG8_BAR; PG8_MMA(1, 1, At, B1); PG8_BAR;
;       PG8_LDB(B0, 1, 0); PG8_SCHED; PG8_LDA(At, 1, 0); PG8_STAGE(PG8_SA(0, 1), a2 + hstep, voffA);
;       PG8_WAIT_L(8); PG8_BAR; PG8_WAIT_L(0); PG8_MMA(0, 0, At, B0); PG8_BAR; PG8_SCHED;
;       PG8_LDB(B1, 1, 1); PG8_STAGE(PG8_SB(1, 0), b3, voffB);
;       PG8_BAR; PG8_WAIT_L(0); PG8_MMA(0, 1, At, B1); PG8_BAR;
;       PG8_LDA(At, 1, 1); PG8_STAGE(PG8_SA(1, 0), a3, voffA);
;       PG8_BAR; PG8_WAIT_L(0); PG8_MMA(1, 0, At, B0); PG8_BAR; PG8_SCHED;
	s_add_u32 s64, s8, 0x40000
	s_addc_u32 s65, s9, 0
	s_add_i32 s63, s55, s45
	v_lshl_add_u64 v[142:143], s[64:65], 0, v[130:131]
	s_mov_b32 m0, s63
	s_nop 0
	global_load_lds_dwordx4 v[142:143], off
	v_lshl_add_u64 v[142:143], s[64:65], 0, v[134:135]
	s_add_i32 m0, s63, 0x2000
	s_nop 0
	global_load_lds_dwordx4 v[142:143], off
	s_waitcnt vmcnt(6)
	s_barrier
	s_setprio 1
	v_mfma_f32_16x16x32_bf16 v[60:63], v[200:203], v[168:171], v[60:63]
	v_mfma_f32_16x16x32_bf16 v[56:59], v[208:211], v[168:171], v[56:59]
	v_mfma_f32_16x16x32_bf16 v[40:43], v[200:203], v[176:179], v[40:43]
	v_mfma_f32_16x16x32_bf16 v[32:35], v[208:211], v[176:179], v[32:35]
	v_mfma_f32_16x16x32_bf16 v[24:27], v[200:203], v[184:187], v[24:27]
	v_mfma_f32_16x16x32_bf16 v[16:19], v[208:211], v[184:187], v[16:19]
	v_mfma_f32_16x16x32_bf16 v[8:11], v[200:203], v[192:195], v[8:11]
	v_mfma_f32_16x16x32_bf16 v[0:3], v[208:211], v[192:195], v[0:3]
	v_mfma_f32_16x16x32_bf16 v[60:63], v[204:207], v[172:175], v[60:63]
	v_mfma_f32_16x16x32_bf16 v[56:59], v[212:215], v[172:175], v[56:59]
	v_mfma_f32_16x16x32_bf16 v[40:43], v[204:207], v[180:183], v[40:43]
	v_mfma_f32_16x16x32_bf16 v[32:35], v[212:215], v[180:183], v[32:35]
	v_mfma_f32_16x16x32_bf16 v[24:27], v[204:207], v[188:191], v[24:27]
	v_mfma_f32_16x16x32_bf16 v[16:19], v[212:215], v[188:191], v[16:19]
	v_mfma_f32_16x16x32_bf16 v[8:11], v[204:207], v[196:199], v[8:11]
	v_mfma_f32_16x16x32_bf16 v[0:3], v[212:215], v[196:199], v[0:3]
	s_setprio 0
	s_add_i32 s63, 0, 0x18000
	v_add_u32_e32 v159, s63, v153
	s_barrier
	ds_read_b128 v[142:145], v159
	ds_read_b128 v[146:149], v159 offset:1024
	ds_read_b128 v[160:163], v159 offset:2048
	ds_read_b128 v[164:167], v159 offset:3072
	s_add_u32 s36, s36, 0x40000
	s_addc_u32 s37, s37, 0
	s_mov_b32 m0, s47
	v_lshl_add_u64 v[200:201], s[36:37], 0, v[128:129]
	ds_read_b128 v[168:171], v156 offset:32768
	ds_read_b128 v[172:175], v156 offset:33792
	ds_read_b128 v[176:179], v156 offset:34816
	ds_read_b128 v[180:183], v156 offset:35840
	ds_read_b128 v[184:187], v156 offset:36864
	ds_read_b128 v[188:191], v156 offset:37888
	ds_read_b128 v[192:195], v156 offset:38912
	ds_read_b128 v[196:199], v156 offset:39936
	global_load_lds_dwordx4 v[200:201], off
	v_lshl_add_u64 v[200:201], s[36:37], 0, v[132:133]
	s_mov_b32 m0, s48
	s_nop 0
	global_load_lds_dwordx4 v[200:201], off
	s_waitcnt lgkmcnt(8)
	s_barrier
	s_waitcnt lgkmcnt(0)
	s_setprio 1
	s_waitcnt lgkmcnt(0)
	v_mfma_f32_16x16x32_bf16 v[116:119], v[142:145], v[168:171], v[116:119]
	v_mfma_f32_16x16x32_bf16 v[112:115], v[160:163], v[168:171], v[112:115]
	v_mfma_f32_16x16x32_bf16 v[108:111], v[142:145], v[176:179], v[108:111]
	v_mfma_f32_16x16x32_bf16 v[100:103], v[160:163], v[176:179], v[100:103]
	v_mfma_f32_16x16x32_bf16 v[92:95], v[142:145], v[184:187], v[92:95]
	v_mfma_f32_16x16x32_bf16 v[84:87], v[160:163], v[184:187], v[84:87]
	v_mfma_f32_16x16x32_bf16 v[76:79], v[142:145], v[192:195], v[76:79]
	v_mfma_f32_16x16x32_bf16 v[68:71], v[160:163], v[192:195], v[68:71]
	v_mfma_f32_16x16x32_bf16 v[116:119], v[146:149], v[172:175], v[116:119]
	v_mfma_f32_16x16x32_bf16 v[112:115], v[164:167], v[172:175], v[112:115]
	v_mfma_f32_16x16x32_bf16 v[108:111], v[146:149], v[180:183], v[108:111]
	v_mfma_f32_16x16x32_bf16 v[100:103], v[164:167], v[180:183], v[100:103]
	v_mfma_f32_16x16x32_bf16 v[92:95], v[146:149], v[188:191], v[92:95]
	v_mfma_f32_16x16x32_bf16 v[84:87], v[164:167], v[188:191], v[84:87]
	v_mfma_f32_16x16x32_bf16 v[76:79], v[146:149], v[196:199], v[76:79]
	v_mfma_f32_16x16x32_bf16 v[68:71], v[164:167], v[196:199], v[68:71]
	s_setprio 0
	s_barrier
	s_add_i32 s36, 0, 0x1c000
	s_add_i32 s37, s63, s45
	v_add_u32_e32 v159, s36, v153
	v_lshl_add_u64 v[150:151], v[150:151], 0, s[20:21]
	s_mov_b32 m0, s37
	ds_read_b128 v[200:203], v159
	ds_read_b128 v[204:207], v159 offset:1024
	ds_read_b128 v[208:211], v159 offset:2048
	ds_read_b128 v[212:215], v159 offset:3072
	global_load_lds_dwordx4 v[150:151], off
	v_lshl_add_u64 v[150:151], v[216:217], 0, s[20:21]
	s_add_i32 m0, s37, 0x2000
	s_nop 0
	global_load_lds_dwordx4 v[150:151], off
	s_barrier
	s_waitcnt lgkmcnt(0)
	s_setprio 1
	s_waitcnt lgkmcnt(0)
	v_mfma_f32_16x16x32_bf16 v[124:127], v[200:203], v[168:171], v[124:127]
	v_mfma_f32_16x16x32_bf16 v[120:123], v[208:211], v[168:171], v[120:123]
	v_mfma_f32_16x16x32_bf16 v[104:107], v[200:203], v[176:179], v[104:107]
	v_mfma_f32_16x16x32_bf16 v[96:99], v[208:211], v[176:179], v[96:99]
	v_mfma_f32_16x16x32_bf16 v[88:91], v[200:203], v[184:187], v[88:91]
	v_mfma_f32_16x16x32_bf16 v[80:83], v[208:211], v[184:187], v[80:83]
	v_mfma_f32_16x16x32_bf16 v[72:75], v[200:203], v[192:195], v[72:75]
	v_mfma_f32_16x16x32_bf16 v[64:67], v[208:211], v[192:195], v[64:67]
	v_mfma_f32_16x16x32_bf16 v[124:127], v[204:207], v[172:175], v[124:127]
	v_mfma_f32_16x16x32_bf16 v[120:123], v[212:215], v[172:175], v[120:123]
	v_mfma_f32_16x16x32_bf16 v[104:107], v[204:207], v[180:183], v[104:107]
	v_mfma_f32_16x16x32_bf16 v[96:99], v[212:215], v[180:183], v[96:99]
	v_mfma_f32_16x16x32_bf16 v[88:91], v[204:207], v[188:191], v[88:91]
	v_mfma_f32_16x16x32_bf16 v[80:83], v[212:215], v[188:191], v[80:83]
	v_mfma_f32_16x16x32_bf16 v[72:75], v[204:207], v[196:199], v[72:75]
	v_mfma_f32_16x16x32_bf16 v[64:67], v[212:215], v[196:199], v[64:67]
	s_setprio 0
	s_mov_b32 m0, s50
	v_lshl_add_u64 v[150:151], v[220:221], 0, s[20:21]
	s_barrier
	ds_read_b128 v[168:171], v156 offset:49152
	ds_read_b128 v[172:175], v156 offset:50176
	ds_read_b128 v[176:179], v156 offset:51200
	ds_read_b128 v[180:183], v156 offset:52224
	ds_read_b128 v[184:187], v156 offset:53248
	ds_read_b128 v[188:191], v156 offset:54272
	ds_read_b128 v[192:195], v156 offset:55296
	ds_read_b128 v[196:199], v156 offset:56320
	global_load_lds_dwordx4 v[150:151], off
	v_lshl_add_u64 v[150:151], v[222:223], 0, s[20:21]
	s_mov_b32 m0, s51
	s_nop 0
	global_load_lds_dwordx4 v[150:151], off
	s_barrier
; #define PG8_STAGE(bufoff, gbase, voff) do { _Pragma("unroll") for (int _i = 0; _i < 2; ++_i) \
;     __builtin_amdgcn_global_load_lds((const unsigned*)((const char*)(gbase) + (voff)[_i]), (PG8_LAS unsigned*)(lds + (bufoff) + ldsw + _i * 8192), 16, 0, 0); } while (0)
; #define PG8_LDA(dst, b, h) do { _Pragma("unroll") for (int m = 0; m < 4; ++m) _Pragma("unroll") for (int k = 0; k < 2; ++k) dst[m][k] = *(const PG8_LAS bf16x8*)(lds + PG8_SA(b, h) + aoff + m * 2048 + k * 1024); } while (0)
; #define PG8_MMA(ai, bj, At, Bt) do { __builtin_amdgcn_s_setprio(1); _Pragma("unroll") for (int m = 0; m < 4; ++m) _Pragma("unroll") for (int n = 0; n < 2; ++n) _Pragma("unroll") for (int k = 0; k < 2; ++k) \
;     acc[ai][bj][m][n] = __builtin_amdgcn_mfma_f32_16x16x32_bf16(Bt[n][k], At[m][k], acc[ai][bj][m][n], 0, 0, 0); __builtin_amdgcn_s_setprio(0); } while (0)
; #define PG8_WAIT_V(n) asm volatile("s_waitcnt vmcnt(" #n ")" ::: "memory")
; #define PG8_WAIT_L(n) asm volatile("s_waitcnt lgkmcnt(" #n ")" ::: "memory")
; #define PG8_BAR __builtin_amdgcn_s_barrier()
; #define PG8_SCHED __builtin_amdgcn_sched_barrier(0)
; #define EPI_ROWS_BEGIN() \
;   _Pragma("unroll") for (int ai = 0; ai < 2; ++ai) { if (u.pm * 256 + ai * 128 >= T) continue;
; template <class Epi>
; DI void gemm_phase(PG8_LAS unsigned char* lds, const Gemm g, const StaticOrder& S, const Epi& E, const int wv) {
;     ...
;       PG8_LDA(At, 1, 1); PG8_STAGE(PG8_SA(1, 0), a3, voffA);
;       PG8_BAR; PG8_WAIT_L(0); PG8_MMA(1, 0, At, B0); PG8_BAR; PG8_SCHED;
;       PG8_STAGE(PG8_SB(1, 1), b3 + hstep, voffB);
;       PG8_WAIT_V(6); PG8_BAR; PG8_MMA(1, 1, At, B1); PG8_BAR;
;     }
;   DI void operator()(AccRef acc, const pg8::Unit& u, int wr, int wc, int fr, int fq) const {
;     const int row0 = u.pm * 256 + wr * 64 + fr, col0 = u.pn * 128 + wc * 32 + 8 * fq;
;     EPI_ROWS_BEGIN()
;       float rs[4];
; #pragma unroll
;       for (int m = 0; m < 4; ++m) rs[m] = ss[row0 + ai * 128 + m * 16];
; #pragma unroll
;       for (int m = 0; m < 4; ++m) rs[m] = rsqrtf(rs[m] * (1.f / DM) + EPS);
; #pragma unroll
;       for (int m = 0; m < 4; ++m) {
;         const int row = row0 + ai * 128 + m * 16;
;         const float ne = rs[m] * -1.4426950408889634f, r2 = rs[m] * rs[m];
	s_waitcnt lgkmcnt(0)
	s_setprio 1
	s_waitcnt lgkmcnt(0)
	v_mfma_f32_16x16x32_bf16 v[52:55], v[142:145], v[168:171], v[52:55]
	v_mfma_f32_16x16x32_bf16 v[48:51], v[160:163], v[168:171], v[48:51]
	v_mfma_f32_16x16x32_bf16 v[44:47], v[142:145], v[176:179], v[44:47]
	v_mfma_f32_16x16x32_bf16 v[36:39], v[160:163], v[176:179], v[36:39]
	v_mfma_f32_16x16x32_bf16 v[28:31], v[142:145], v[184:187], v[28:31]
	v_mfma_f32_16x16x32_bf16 v[20:23], v[160:163], v[184:187], v[20:23]
	v_mfma_f32_16x16x32_bf16 v[12:15], v[142:145], v[192:195], v[12:15]
	v_mfma_f32_16x16x32_bf16 v[4:7], v[160:163], v[192:195], v[4:7]
	v_mfma_f32_16x16x32_bf16 v[52:55], v[146:149], v[172:175], v[52:55]
	v_mfma_f32_16x16x32_bf16 v[48:51], v[164:167], v[172:175], v[48:51]
	v_mfma_f32_16x16x32_bf16 v[44:47], v[146:149], v[180:183], v[44:47]
	v_mfma_f32_16x16x32_bf16 v[36:39], v[164:167], v[180:183], v[36:39]
	v_mfma_f32_16x16x32_bf16 v[28:31], v[146:149], v[188:191], v[28:31]
	v_mfma_f32_16x16x32_bf16 v[20:23], v[164:167], v[188:191], v[20:23]
	v_mfma_f32_16x16x32_bf16 v[12:15], v[146:149], v[196:199], v[12:15]
	v_mfma_f32_16x16x32_bf16 v[4:7], v[164:167], v[196:199], v[4:7]
	s_setprio 0
	s_barrier
	s_add_u32 s8, s8, 0x40080
	s_addc_u32 s9, s9, 0
	s_add_i32 s36, s36, s45
	v_lshl_add_u64 v[142:143], s[8:9], 0, v[130:131]
	s_mov_b32 m0, s36
	s_nop 0
	global_load_lds_dwordx4 v[142:143], off
	v_lshl_add_u64 v[142:143], s[8:9], 0, v[134:135]
	s_add_i32 m0, s36, 0x2000
	s_nop 0
	global_load_lds_dwordx4 v[142:143], off
	s_waitcnt vmcnt(6)
	s_barrier
	s_setprio 1
	v_mfma_f32_16x16x32_bf16 v[60:63], v[200:203], v[168:171], v[60:63]
	v_mfma_f32_16x16x32_bf16 v[56:59], v[208:211], v[168:171], v[56:59]
	v_mfma_f32_16x16x32_bf16 v[40:43], v[200:203], v[176:179], v[40:43]
	v_mfma_f32_16x16x32_bf16 v[32:35], v[208:211], v[176:179], v[32:35]
	v_mfma_f32_16x16x32_bf16 v[24:27], v[200:203], v[184:187], v[24:27]
	v_mfma_f32_16x16x32_bf16 v[16:19], v[208:211], v[184:187], v[16:19]
	v_mfma_f32_16x16x32_bf16 v[8:11], v[200:203], v[192:195], v[8:11]
	v_mfma_f32_16x16x32_bf16 v[0:3], v[208:211], v[192:195], v[0:3]
	v_mfma_f32_16x16x32_bf16 v[60:63], v[204:207], v[172:175], v[60:63]
	v_mfma_f32_16x16x32_bf16 v[56:59], v[212:215], v[172:175], v[56:59]
	v_mfma_f32_16x16x32_bf16 v[40:43], v[204:207], v[180:183], v[40:43]
	v_mfma_f32_16x16x32_bf16 v[32:35], v[212:215], v[180:183], v[32:35]
	v_mfma_f32_16x16x32_bf16 v[24:27], v[204:207], v[188:191], v[24:27]
	v_mfma_f32_16x16x32_bf16 v[16:19], v[212:215], v[188:191], v[16:19]
	v_mfma_f32_16x16x32_bf16 v[8:11], v[204:207], v[196:199], v[8:11]
	v_mfma_f32_16x16x32_bf16 v[0:3], v[212:215], v[196:199], v[0:3]
	s_setprio 0
	s_add_i32 s62, s62, 2
	s_add_u32 s6, s6, 0x100
	s_addc_u32 s7, s7, 0
	s_add_u32 s60, s60, 0x100
	s_addc_u32 s61, s61, 0
	s_cmp_gt_u32 s62, 13
	s_barrier
	s_cbranch_scc0 .LBB0_893
	v_lshl_or_b32 v142, s4, 7, v154
	v_ashrrev_i32_e32 v143, 31, v142
	v_lshl_add_u32 v144, s34, 8, v152
	s_cmpk_gt_i32 s34, 0x181
	v_lshlrev_b64 v[142:143], 1, v[142:143]
	s_cbranch_scc1 .LBB0_896
	v_ashrrev_i32_e32 v145, 31, v144
	v_lshl_add_u64 v[146:147], v[144:145], 2, s[18:19]
	v_or_b32_e32 v150, 16, v144
	global_load_dword v145, v[146:147], off
	v_ashrrev_i32_e32 v151, 31, v150
	v_or_b32_e32 v148, 32, v144
	v_or_b32_e32 v146, 48, v144
	v_lshl_add_u64 v[160:161], v[150:151], 2, s[18:19]
	v_ashrrev_i32_e32 v149, 31, v148
	v_ashrrev_i32_e32 v147, 31, v146
	v_lshl_add_u64 v[162:163], v[148:149], 2, s[18:19]
	v_lshl_add_u64 v[164:165], v[146:147], 2, s[18:19]
	global_load_dword v147, v[160:161], off
	global_load_dword v149, v[162:163], off
	global_load_dword v151, v[164:165], off
	v_add_u32_e32 v224, 0x80, v144
	v_ashrrev_i32_e32 v225, 31, v224
	v_lshl_add_u64 v[226:227], v[224:225], 2, s[18:19]
	global_load_dword v250, v[226:227], off
	global_load_dword v251, v[226:227], off offset:64
	global_load_dword v252, v[226:227], off offset:128
	global_load_dword v253, v[226:227], off offset:192
	v_pk_mul_f32 v[160:161], v[112:113], v[120:121]
	v_mov_b64_e32 v[120:121], s[16:17]
	v_mad_i64_i32 v[162:163], s[4:5], v144, s58, v[120:121]
	v_pk_mul_f32 v[126:127], v[118:119], v[126:127]
	v_pk_mul_f32 v[124:125], v[116:117], v[124:125]
	v_pk_mul_f32 v[122:123], v[114:115], v[122:123]
	v_pk_mul_f32 v[104:105], v[108:109], v[104:105]
	v_pk_mul_f32 v[106:107], v[110:111], v[106:107]
	v_pk_mul_f32 v[98:99], v[102:103], v[98:99]
	v_lshl_add_u64 v[162:163], v[162:163], 0, v[142:143]
	v_pk_mul_f32 v[96:97], v[100:101], v[96:97]
	v_pk_mul_f32 v[88:89], v[92:93], v[88:89]
	v_pk_mul_f32 v[90:91], v[94:95], v[90:91]
	v_pk_mul_f32 v[82:83], v[86:87], v[82:83]
	v_pk_mul_f32 v[80:81], v[84:85], v[80:81]
	v_pk_mul_f32 v[72:73], v[76:77], v[72:73]
	v_pk_mul_f32 v[74:75], v[78:79], v[74:75]
	v_pk_mul_f32 v[66:67], v[70:71], v[66:67]
	v_pk_mul_f32 v[64:65], v[68:69], v[64:65]
	s_waitcnt vmcnt(4)
; DI u32x4 pack8v(f32x4 a, f32x4 b) { return u32x4{cvtpk(a[0], a[1]), cvtpk(a[2], a[3]), cvtpk(b[0], b[1]), cvtpk(b[2], b[3])}; }
;   DI void operator()(AccRef acc, const pg8::Unit& u, int wr, int wc, int fr, int fq) const {
;     ...
;       for (int m = 0; m < 4; ++m) rs[m] = ss[row0 + ai * 128 + m * 16];
; #pragma unroll
;       for (int m = 0; m < 4; ++m) rs[m] = rsqrtf(rs[m] * (1.f / DM) + EPS);
; #pragma unroll
;       for (int m = 0; m < 4; ++m) {
;         const int row = row0 + ai * 128 + m * 16;
;         const float ne = rs[m] * -1.4426950408889634f, r2 = rs[m] * rs[m];
;         f32x4 y[2];
; #pragma unroll
;         for (int n = 0; n < 2; ++n)
; #pragma unroll
;           for (int e = 0; e < 4; ++e) {
;             const float a = acc[ai][0][m][n][e], b = acc[ai][1][m][n][e];
;             y[n][e] = a * b * r2 * __builtin_amdgcn_rcpf(1.f + __builtin_amdgcn_exp2f(a * ne));
;           }
;         *(u32x4*)(act + (size_t)row * FFN + col0) = pack8v(y[0], y[1]);
	v_fmamk_f32 v145, v145, 0x3a800000, v158
	v_mul_f32_e32 v159, 0x4b800000, v145
	v_cmp_gt_f32_e32 vcc, s57, v145
	v_fmamk_f32 v147, v147, 0x3a800000, v158
	v_fmamk_f32 v149, v149, 0x3a800000, v158
	v_fmamk_f32 v151, v151, 0x3a800000, v158
	v_cndmask_b32_e32 v145, v145, v159, vcc
	v_mul_f32_e32 v159, 0x4b800000, v147
	v_cmp_gt_f32_e64 s[4:5], s57, v147
	v_mul_f32_e32 v164, 0x4b800000, v149
	v_mul_f32_e32 v165, 0x4b800000, v151
	v_rsq_f32_e32 v145, v145
	v_cndmask_b32_e64 v147, v147, v159, s[4:5]
	v_cmp_gt_f32_e64 s[6:7], s57, v149
	v_cmp_gt_f32_e64 s[8:9], s57, v151
	v_rsq_f32_e32 v147, v147
	v_cndmask_b32_e64 v149, v149, v164, s[6:7]
	v_cndmask_b32_e64 v151, v151, v165, s[8:9]
	v_rsq_f32_e32 v149, v149
	v_rsq_f32_e32 v151, v151
	v_mul_f32_e32 v159, 0x45800000, v145
	v_cndmask_b32_e32 v145, v145, v159, vcc
	v_mul_f32_e32 v159, 0x45800000, v147
	v_mul_f32_e32 v164, 0x45800000, v149
	v_mul_f32_e32 v165, 0x45800000, v151
	v_cndmask_b32_e64 v147, v147, v159, s[4:5]
	v_mul_f32_e32 v159, 0xbfb8aa3b, v145
	v_cndmask_b32_e64 v149, v149, v164, s[6:7]
	v_cndmask_b32_e64 v151, v151, v165, s[8:9]
	v_mul_f32_e32 v164, v145, v145
	v_mul_f32_e32 v165, v117, v159
	v_mul_f32_e32 v145, v116, v159
	v_pk_mul_f32 v[116:117], v[124:125], v[164:165] op_sel_hi:[1,0]
	v_mul_f32_e32 v124, v118, v159
	v_mul_f32_e32 v125, v119, v159
	v_pk_mul_f32 v[118:119], v[126:127], v[164:165] op_sel_hi:[1,0]
	v_mul_f32_e32 v126, v112, v159
	v_mul_f32_e32 v127, v113, v159
	v_pk_mul_f32 v[112:113], v[160:161], v[164:165] op_sel_hi:[1,0]
	v_mul_f32_e32 v160, v114, v159
	v_mul_f32_e32 v159, v115, v159
	v_pk_mul_f32 v[114:115], v[122:123], v[164:165] op_sel_hi:[1,0]
	v_mul_f32_e32 v123, 0xbfb8aa3b, v147
	v_mul_f32_e32 v161, v108, v123
	v_mul_f32_e32 v164, v109, v123
	v_mul_f32_e32 v108, v110, v123
	v_mul_f32_e32 v109, v111, v123
	v_mul_f32_e32 v122, v147, v147
	v_exp_f32_e32 v145, v145
	v_exp_f32_e32 v147, v165
	v_exp_f32_e32 v124, v124
	v_exp_f32_e32 v125, v125
	v_exp_f32_e32 v126, v126
	v_exp_f32_e32 v127, v127
	v_exp_f32_e32 v160, v160
	v_exp_f32_e32 v159, v159
	v_exp_f32_e32 v108, v108
	v_exp_f32_e32 v109, v109
	v_exp_f32_e32 v166, v161
	v_exp_f32_e32 v167, v164
	v_add_f32_e32 v145, 1.0, v145
	v_add_f32_e32 v147, 1.0, v147
	v_add_f32_e32 v161, 1.0, v124
	v_add_f32_e32 v164, 1.0, v125
	v_add_f32_e32 v165, 1.0, v126
	v_add_f32_e32 v168, 1.0, v127
	v_add_f32_e32 v169, 1.0, v160
	v_add_f32_e32 v159, 1.0, v159
	v_add_f32_e32 v108, 1.0, v108
	v_add_f32_e32 v109, 1.0, v109
	v_mul_f32_e32 v110, v100, v123
	v_mul_f32_e32 v111, v101, v123
	v_rcp_f32_e32 v124, v145
	v_rcp_f32_e32 v125, v147
	v_rcp_f32_e32 v126, v161
	v_rcp_f32_e32 v127, v164
	v_rcp_f32_e32 v160, v165
	v_rcp_f32_e32 v161, v168
	v_rcp_f32_e32 v164, v169
	v_rcp_f32_e32 v165, v159
	v_rcp_f32_e32 v108, v108
	v_rcp_f32_e32 v109, v109
	v_exp_f32_e32 v110, v110
	v_exp_f32_e32 v111, v111
	v_mul_f32_e32 v102, v102, v123
	v_mul_f32_e32 v103, v103, v123
	v_exp_f32_e32 v102, v102
	v_exp_f32_e32 v103, v103
	v_pk_mul_f32 v[106:107], v[106:107], v[122:123] op_sel_hi:[1,0]
	v_pk_mul_f32 v[116:117], v[116:117], v[124:125]
	v_pk_mul_f32 v[118:119], v[118:119], v[126:127]
	v_pk_mul_f32 v[124:125], v[112:113], v[160:161]
	v_pk_mul_f32 v[126:127], v[114:115], v[164:165]
	v_pk_mul_f32 v[106:107], v[106:107], v[108:109]
	v_add_f32_e32 v108, 1.0, v110
	v_add_f32_e32 v109, 1.0, v111
	v_cvt_pk_bf16_f32 v112, v116, v117
	v_cvt_pk_bf16_f32 v113, v118, v119
	v_cvt_pk_bf16_f32 v114, v124, v125
	v_cvt_pk_bf16_f32 v115, v126, v127
	v_rcp_f32_e32 v108, v108
	v_rcp_f32_e32 v109, v109
	v_add_f32_e32 v100, 1.0, v102
	v_add_f32_e32 v101, 1.0, v103
	v_add_f32_e32 v145, 1.0, v166
	global_store_dwordx4 v[162:163], v[112:115], off
	v_rcp_f32_e32 v100, v100
	v_rcp_f32_e32 v101, v101
	v_add_f32_e32 v113, 1.0, v167
	v_rcp_f32_e32 v112, v145
	v_rcp_f32_e32 v113, v113
	v_pk_mul_f32 v[96:97], v[96:97], v[122:123] op_sel_hi:[1,0]
	v_pk_mul_f32 v[104:105], v[104:105], v[122:123] op_sel_hi:[1,0]
	v_pk_mul_f32 v[102:103], v[96:97], v[108:109]
	v_pk_mul_f32 v[96:97], v[98:99], v[122:123] op_sel_hi:[1,0]
	v_pk_mul_f32 v[104:105], v[104:105], v[112:113]
	v_pk_mul_f32 v[100:101], v[96:97], v[100:101]
	v_cvt_pk_bf16_f32 v96, v104, v105
	v_cvt_pk_bf16_f32 v99, v100, v101
	v_mad_i64_i32 v[100:101], s[4:5], v150, s58, v[120:121]
	v_cvt_pk_bf16_f32 v97, v106, v107
	v_cvt_pk_bf16_f32 v98, v102, v103
	v_lshl_add_u64 v[100:101], v[100:101], 0, v[142:143]
	global_store_dwordx4 v[100:101], v[96:99], off
	s_nop 1
	v_mul_f32_e32 v97, 0xbfb8aa3b, v149
	v_mul_f32_e32 v96, v92, v97
	v_exp_f32_e32 v98, v96
	v_mul_f32_e32 v96, v93, v97
	v_mul_f32_e32 v92, v94, v97
	v_mul_f32_e32 v93, v95, v97
	v_exp_f32_e32 v92, v92
	v_exp_f32_e32 v93, v93
	v_mul_f32_e32 v94, v84, v97
	v_mul_f32_e32 v95, v85, v97
	v_add_f32_e32 v92, 1.0, v92
	v_add_f32_e32 v93, 1.0, v93
	v_rcp_f32_e32 v92, v92
	v_rcp_f32_e32 v93, v93
	v_exp_f32_e32 v94, v94
	v_exp_f32_e32 v95, v95
	v_mul_f32_e32 v86, v86, v97
	v_mul_f32_e32 v87, v87, v97
	v_exp_f32_e32 v86, v86
	v_exp_f32_e32 v87, v87
	v_exp_f32_e32 v99, v96
	v_mul_f32_e32 v96, v149, v149
	v_pk_mul_f32 v[90:91], v[90:91], v[96:97] op_sel_hi:[1,0]
	v_add_f32_e32 v84, 1.0, v86
	v_pk_mul_f32 v[90:91], v[90:91], v[92:93]
	v_add_f32_e32 v92, 1.0, v94
	v_add_f32_e32 v93, 1.0, v95
	v_rcp_f32_e32 v92, v92
	v_rcp_f32_e32 v93, v93
	v_add_f32_e32 v85, 1.0, v87
	v_add_f32_e32 v98, 1.0, v98
	v_add_f32_e32 v99, 1.0, v99
	v_rcp_f32_e32 v84, v84
	v_rcp_f32_e32 v85, v85
	v_rcp_f32_e32 v98, v98
	v_rcp_f32_e32 v99, v99
	v_pk_mul_f32 v[80:81], v[80:81], v[96:97] op_sel_hi:[1,0]
	v_pk_mul_f32 v[88:89], v[88:89], v[96:97] op_sel_hi:[1,0]
	v_pk_mul_f32 v[86:87], v[80:81], v[92:93]
; DI u32x4 pack8v(f32x4 a, f32x4 b) { return u32x4{cvtpk(a[0], a[1]), cvtpk(a[2], a[3]), cvtpk(b[0], b[1]), cvtpk(b[2], b[3])}; }
; #define EPI_ROWS_BEGIN() \
;   _Pragma("unroll") for (int ai = 0; ai < 2; ++ai) { if (u.pm * 256 + ai * 128 >= T) continue;
;   DI void operator()(AccRef acc, const pg8::Unit& u, int wr, int wc, int fr, int fq) const {
;     ...
;     EPI_ROWS_BEGIN()
;       float rs[4];
; #pragma unroll
;       for (int m = 0; m < 4; ++m) rs[m] = ss[row0 + ai * 128 + m * 16];
; #pragma unroll
;       for (int m = 0; m < 4; ++m) rs[m] = rsqrtf(rs[m] * (1.f / DM) + EPS);
; #pragma unroll
;       for (int m = 0; m < 4; ++m) {
;         const int row = row0 + ai * 128 + m * 16;
;         const float ne = rs[m] * -1.4426950408889634f, r2 = rs[m] * rs[m];
;         f32x4 y[2];
; #pragma unroll
;         for (int n = 0; n < 2; ++n)
; #pragma unroll
;           for (int e = 0; e < 4; ++e) {
;             const float a = acc[ai][0][m][n][e], b = acc[ai][1][m][n][e];
;             y[n][e] = a * b * r2 * __builtin_amdgcn_rcpf(1.f + __builtin_amdgcn_exp2f(a * ne));
;           }
;         *(u32x4*)(act + (size_t)row * FFN + col0) = pack8v(y[0], y[1]);
	v_pk_mul_f32 v[80:81], v[82:83], v[96:97] op_sel_hi:[1,0]
	v_pk_mul_f32 v[88:89], v[88:89], v[98:99]
	v_pk_mul_f32 v[84:85], v[80:81], v[84:85]
	v_cvt_pk_bf16_f32 v80, v88, v89
	v_cvt_pk_bf16_f32 v83, v84, v85
	v_mad_i64_i32 v[84:85], s[4:5], v148, s58, v[120:121]
	v_cvt_pk_bf16_f32 v81, v90, v91
	v_cvt_pk_bf16_f32 v82, v86, v87
	v_lshl_add_u64 v[84:85], v[84:85], 0, v[142:143]
	global_store_dwordx4 v[84:85], v[80:83], off
	s_nop 1
	v_mul_f32_e32 v81, 0xbfb8aa3b, v151
	v_mul_f32_e32 v80, v76, v81
	v_exp_f32_e32 v82, v80
	v_mul_f32_e32 v80, v77, v81
	v_mul_f32_e32 v76, v78, v81
	v_mul_f32_e32 v77, v79, v81
	v_exp_f32_e32 v76, v76
	v_exp_f32_e32 v77, v77
	v_mul_f32_e32 v78, v68, v81
	v_mul_f32_e32 v79, v69, v81
	v_add_f32_e32 v76, 1.0, v76
	v_add_f32_e32 v77, 1.0, v77
	v_rcp_f32_e32 v76, v76
	v_rcp_f32_e32 v77, v77
	v_exp_f32_e32 v78, v78
	v_exp_f32_e32 v79, v79
	v_mul_f32_e32 v70, v70, v81
	v_mul_f32_e32 v71, v71, v81
	v_exp_f32_e32 v70, v70
	v_exp_f32_e32 v71, v71
	v_exp_f32_e32 v83, v80
	v_mul_f32_e32 v80, v151, v151
	v_pk_mul_f32 v[74:75], v[74:75], v[80:81] op_sel_hi:[1,0]
	v_add_f32_e32 v68, 1.0, v70
	v_pk_mul_f32 v[74:75], v[74:75], v[76:77]
	v_add_f32_e32 v76, 1.0, v78
	v_add_f32_e32 v77, 1.0, v79
	v_rcp_f32_e32 v76, v76
	v_rcp_f32_e32 v77, v77
	v_add_f32_e32 v69, 1.0, v71
	v_add_f32_e32 v82, 1.0, v82
	v_add_f32_e32 v83, 1.0, v83
	v_rcp_f32_e32 v68, v68
	v_rcp_f32_e32 v69, v69
	v_rcp_f32_e32 v82, v82
	v_rcp_f32_e32 v83, v83
	v_pk_mul_f32 v[64:65], v[64:65], v[80:81] op_sel_hi:[1,0]
	v_pk_mul_f32 v[72:73], v[72:73], v[80:81] op_sel_hi:[1,0]
	v_pk_mul_f32 v[70:71], v[64:65], v[76:77]
	v_pk_mul_f32 v[64:65], v[66:67], v[80:81] op_sel_hi:[1,0]
	v_pk_mul_f32 v[72:73], v[72:73], v[82:83]
	v_pk_mul_f32 v[68:69], v[64:65], v[68:69]
	v_cvt_pk_bf16_f32 v64, v72, v73
	v_cvt_pk_bf16_f32 v67, v68, v69
	v_mad_i64_i32 v[68:69], s[4:5], v146, s58, v[120:121]
	v_cvt_pk_bf16_f32 v65, v74, v75
	v_cvt_pk_bf16_f32 v66, v70, v71
	v_lshl_add_u64 v[68:69], v[68:69], 0, v[142:143]
	global_store_dwordx4 v[68:69], v[64:67], off
.LBB0_896:
	s_cmpk_gt_i32 s34, 0x180
	s_cbranch_scc1 .LBB0_885
	v_add_u32_e32 v70, 0x80, v144
	v_ashrrev_i32_e32 v71, 31, v70
	v_add_u32_e32 v68, 0x90, v144
	v_add_u32_e32 v66, 0xa0, v144
	v_add_u32_e32 v64, 0xb0, v144
	v_lshl_add_u64 v[72:73], v[70:71], 2, s[18:19]
	v_ashrrev_i32_e32 v69, 31, v68
	v_ashrrev_i32_e32 v67, 31, v66
	v_ashrrev_i32_e32 v65, 31, v64
	v_lshl_add_u64 v[74:75], v[68:69], 2, s[18:19]
	v_lshl_add_u64 v[76:77], v[66:67], 2, s[18:19]
	v_lshl_add_u64 v[78:79], v[64:65], 2, s[18:19]
	v_pk_mul_f32 v[72:73], v[48:49], v[56:57]
	v_mov_b64_e32 v[56:57], s[16:17]
	v_mad_i64_i32 v[70:71], s[4:5], v70, s58, v[56:57]
	v_pk_mul_f32 v[62:63], v[54:55], v[62:63]
	v_pk_mul_f32 v[60:61], v[52:53], v[60:61]
	v_pk_mul_f32 v[58:59], v[50:51], v[58:59]
	v_pk_mul_f32 v[40:41], v[44:45], v[40:41]
	v_pk_mul_f32 v[42:43], v[46:47], v[42:43]
	v_pk_mul_f32 v[34:35], v[38:39], v[34:35]
	v_lshl_add_u64 v[70:71], v[70:71], 0, v[142:143]
	v_pk_mul_f32 v[32:33], v[36:37], v[32:33]
	v_pk_mul_f32 v[24:25], v[28:29], v[24:25]
	v_pk_mul_f32 v[26:27], v[30:31], v[26:27]
	v_pk_mul_f32 v[18:19], v[22:23], v[18:19]
	v_pk_mul_f32 v[16:17], v[20:21], v[16:17]
	v_pk_mul_f32 v[8:9], v[12:13], v[8:9]
	v_pk_mul_f32 v[10:11], v[14:15], v[10:11]
	v_pk_mul_f32 v[2:3], v[6:7], v[2:3]
	v_pk_mul_f32 v[0:1], v[4:5], v[0:1]
	s_waitcnt vmcnt(4)
	v_fmamk_f32 v65, v250, 0x3a800000, v158
	v_fmamk_f32 v67, v251, 0x3a800000, v158
	v_fmamk_f32 v69, v252, 0x3a800000, v158
	v_fmamk_f32 v74, v253, 0x3a800000, v158
	v_mul_f32_e32 v75, 0x4b800000, v65
	v_mul_f32_e32 v76, 0x4b800000, v67
	v_cmp_gt_f32_e32 vcc, s57, v65
	v_cmp_gt_f32_e64 s[4:5], s57, v67
	v_mul_f32_e32 v77, 0x4b800000, v69
	v_mul_f32_e32 v78, 0x4b800000, v74
	v_cndmask_b32_e32 v65, v65, v75, vcc
	v_cndmask_b32_e64 v67, v67, v76, s[4:5]
	v_cmp_gt_f32_e64 s[6:7], s57, v69
	v_cmp_gt_f32_e64 s[8:9], s57, v74
	v_rsq_f32_e32 v65, v65
	v_cndmask_b32_e64 v69, v69, v77, s[6:7]
	v_cndmask_b32_e64 v74, v74, v78, s[8:9]
	v_rsq_f32_e32 v67, v67
	v_rsq_f32_e32 v69, v69
	v_rsq_f32_e32 v74, v74
	v_mul_f32_e32 v75, 0x45800000, v65
	v_mul_f32_e32 v76, 0x45800000, v67
	v_mul_f32_e32 v77, 0x45800000, v69
	v_mul_f32_e32 v78, 0x45800000, v74
	v_cndmask_b32_e32 v65, v65, v75, vcc
	v_cndmask_b32_e64 v67, v67, v76, s[4:5]
	v_cndmask_b32_e64 v69, v69, v77, s[6:7]
	v_cndmask_b32_e64 v75, v74, v78, s[8:9]
	v_mul_f32_e32 v77, 0xbfb8aa3b, v65
	v_mul_f32_e32 v74, v65, v65
	v_mul_f32_e32 v65, 0xbfb8aa3b, v67
	v_mul_f32_e32 v76, v67, v67
	v_mul_f32_e32 v67, v52, v77
	v_mul_f32_e32 v78, v53, v77
	v_pk_mul_f32 v[52:53], v[60:61], v[74:75] op_sel_hi:[1,0]
	v_mul_f32_e32 v60, v54, v77
	v_mul_f32_e32 v61, v55, v77
	v_pk_mul_f32 v[54:55], v[62:63], v[74:75] op_sel_hi:[1,0]
	v_mul_f32_e32 v62, v48, v77
	v_mul_f32_e32 v63, v49, v77
	v_pk_mul_f32 v[48:49], v[72:73], v[74:75] op_sel_hi:[1,0]
	v_mul_f32_e32 v72, v50, v77
	v_mul_f32_e32 v73, v51, v77
	v_pk_mul_f32 v[50:51], v[58:59], v[74:75] op_sel_hi:[1,0]
	v_mul_f32_e32 v58, v44, v65
	v_mul_f32_e32 v59, v45, v65
	v_mul_f32_e32 v44, v46, v65
	v_mul_f32_e32 v45, v47, v65
	v_exp_f32_e32 v67, v67
	v_exp_f32_e32 v74, v78
	v_exp_f32_e32 v60, v60
	v_exp_f32_e32 v61, v61
	v_exp_f32_e32 v62, v62
	v_exp_f32_e32 v63, v63
	v_exp_f32_e32 v72, v72
	v_exp_f32_e32 v73, v73
	v_exp_f32_e32 v44, v44
	v_exp_f32_e32 v45, v45
; DI u32x4 pack8v(f32x4 a, f32x4 b) { return u32x4{cvtpk(a[0], a[1]), cvtpk(a[2], a[3]), cvtpk(b[0], b[1]), cvtpk(b[2], b[3])}; }
;   DI void operator()(AccRef acc, const pg8::Unit& u, int wr, int wc, int fr, int fq) const {
;     ...
; #pragma unroll
;       for (int m = 0; m < 4; ++m) {
;         const int row = row0 + ai * 128 + m * 16;
;         const float ne = rs[m] * -1.4426950408889634f, r2 = rs[m] * rs[m];
;         f32x4 y[2];
; #pragma unroll
;         for (int n = 0; n < 2; ++n)
; #pragma unroll
;           for (int e = 0; e < 4; ++e) {
;             const float a = acc[ai][0][m][n][e], b = acc[ai][1][m][n][e];
;             y[n][e] = a * b * r2 * __builtin_amdgcn_rcpf(1.f + __builtin_amdgcn_exp2f(a * ne));
;           }
;         *(u32x4*)(act + (size_t)row * FFN + col0) = pack8v(y[0], y[1]);
;       }
	v_exp_f32_e32 v58, v58
	v_exp_f32_e32 v77, v59
	v_add_f32_e32 v59, 1.0, v67
	v_add_f32_e32 v67, 1.0, v74
	v_add_f32_e32 v60, 1.0, v60
	v_add_f32_e32 v61, 1.0, v61
	v_add_f32_e32 v62, 1.0, v62
	v_add_f32_e32 v63, 1.0, v63
	v_add_f32_e32 v72, 1.0, v72
	v_add_f32_e32 v73, 1.0, v73
	v_add_f32_e32 v44, 1.0, v44
	v_add_f32_e32 v45, 1.0, v45
	v_mul_f32_e32 v46, v36, v65
	v_mul_f32_e32 v47, v37, v65
	v_add_f32_e32 v74, 1.0, v58
	v_rcp_f32_e32 v58, v59
	v_rcp_f32_e32 v59, v67
	v_rcp_f32_e32 v60, v60
	v_rcp_f32_e32 v61, v61
	v_rcp_f32_e32 v62, v62
	v_rcp_f32_e32 v63, v63
	v_rcp_f32_e32 v72, v72
	v_rcp_f32_e32 v73, v73
	v_rcp_f32_e32 v44, v44
	v_rcp_f32_e32 v45, v45
	v_exp_f32_e32 v46, v46
	v_exp_f32_e32 v47, v47
	v_mul_f32_e32 v38, v38, v65
	v_mul_f32_e32 v39, v39, v65
	v_exp_f32_e32 v38, v38
	v_exp_f32_e32 v39, v39
	v_pk_mul_f32 v[42:43], v[42:43], v[76:77] op_sel_hi:[1,0]
	v_pk_mul_f32 v[52:53], v[52:53], v[58:59]
	v_pk_mul_f32 v[54:55], v[54:55], v[60:61]
	v_pk_mul_f32 v[58:59], v[48:49], v[62:63]
	v_pk_mul_f32 v[60:61], v[50:51], v[72:73]
	v_pk_mul_f32 v[42:43], v[42:43], v[44:45]
	v_add_f32_e32 v44, 1.0, v46
	v_add_f32_e32 v45, 1.0, v47
	v_cvt_pk_bf16_f32 v48, v52, v53
	v_cvt_pk_bf16_f32 v49, v54, v55
	v_cvt_pk_bf16_f32 v50, v58, v59
	v_cvt_pk_bf16_f32 v51, v60, v61
	v_rcp_f32_e32 v44, v44
	v_rcp_f32_e32 v45, v45
	v_add_f32_e32 v36, 1.0, v38
	v_add_f32_e32 v37, 1.0, v39
	global_store_dwordx4 v[70:71], v[48:51], off
	v_rcp_f32_e32 v36, v36
	v_rcp_f32_e32 v37, v37
	v_add_f32_e32 v49, 1.0, v77
	v_rcp_f32_e32 v48, v74
	v_rcp_f32_e32 v49, v49
	v_pk_mul_f32 v[32:33], v[32:33], v[76:77] op_sel_hi:[1,0]
	v_pk_mul_f32 v[40:41], v[40:41], v[76:77] op_sel_hi:[1,0]
	v_pk_mul_f32 v[38:39], v[32:33], v[44:45]
	v_pk_mul_f32 v[32:33], v[34:35], v[76:77] op_sel_hi:[1,0]
	v_pk_mul_f32 v[40:41], v[40:41], v[48:49]
	v_pk_mul_f32 v[36:37], v[32:33], v[36:37]
	v_cvt_pk_bf16_f32 v32, v40, v41
	v_cvt_pk_bf16_f32 v35, v36, v37
	v_mad_i64_i32 v[36:37], s[4:5], v68, s58, v[56:57]
	v_cvt_pk_bf16_f32 v33, v42, v43
	v_cvt_pk_bf16_f32 v34, v38, v39
	v_lshl_add_u64 v[36:37], v[36:37], 0, v[142:143]
	global_store_dwordx4 v[36:37], v[32:35], off
	s_nop 1
	v_mul_f32_e32 v33, 0xbfb8aa3b, v69
	v_mul_f32_e32 v32, v28, v33
	v_exp_f32_e32 v34, v32
	v_mul_f32_e32 v32, v29, v33
	v_mul_f32_e32 v28, v30, v33
	v_mul_f32_e32 v29, v31, v33
	v_exp_f32_e32 v28, v28
	v_exp_f32_e32 v29, v29
	v_mul_f32_e32 v30, v20, v33
	v_mul_f32_e32 v31, v21, v33
	v_add_f32_e32 v28, 1.0, v28
	v_add_f32_e32 v29, 1.0, v29
	v_rcp_f32_e32 v28, v28
	v_rcp_f32_e32 v29, v29
	v_exp_f32_e32 v30, v30
	v_exp_f32_e32 v31, v31
	v_mul_f32_e32 v22, v22, v33
	v_mul_f32_e32 v23, v23, v33
	v_exp_f32_e32 v22, v22
	v_exp_f32_e32 v23, v23
	v_exp_f32_e32 v35, v32
	v_mul_f32_e32 v32, v69, v69
	v_pk_mul_f32 v[26:27], v[26:27], v[32:33] op_sel_hi:[1,0]
	v_add_f32_e32 v20, 1.0, v22
	v_pk_mul_f32 v[26:27], v[26:27], v[28:29]
	v_add_f32_e32 v28, 1.0, v30
	v_add_f32_e32 v29, 1.0, v31
	v_rcp_f32_e32 v28, v28
	v_rcp_f32_e32 v29, v29
	v_add_f32_e32 v21, 1.0, v23
	v_add_f32_e32 v34, 1.0, v34
	v_add_f32_e32 v35, 1.0, v35
	v_rcp_f32_e32 v20, v20
	v_rcp_f32_e32 v21, v21
	v_rcp_f32_e32 v34, v34
	v_rcp_f32_e32 v35, v35
	v_pk_mul_f32 v[16:17], v[16:17], v[32:33] op_sel_hi:[1,0]
	v_pk_mul_f32 v[24:25], v[24:25], v[32:33] op_sel_hi:[1,0]
	v_pk_mul_f32 v[22:23], v[16:17], v[28:29]
	v_pk_mul_f32 v[16:17], v[18:19], v[32:33] op_sel_hi:[1,0]
	v_pk_mul_f32 v[24:25], v[24:25], v[34:35]
	v_pk_mul_f32 v[20:21], v[16:17], v[20:21]
	v_cvt_pk_bf16_f32 v16, v24, v25
	v_cvt_pk_bf16_f32 v19, v20, v21
	v_mad_i64_i32 v[20:21], s[4:5], v66, s58, v[56:57]
	v_cvt_pk_bf16_f32 v17, v26, v27
	v_cvt_pk_bf16_f32 v18, v22, v23
	v_lshl_add_u64 v[20:21], v[20:21], 0, v[142:143]
	global_store_dwordx4 v[20:21], v[16:19], off
	s_nop 1
	v_mul_f32_e32 v17, 0xbfb8aa3b, v75
	v_mul_f32_e32 v16, v12, v17
	v_exp_f32_e32 v18, v16
	v_mul_f32_e32 v16, v13, v17
	v_mul_f32_e32 v12, v14, v17
	v_mul_f32_e32 v13, v15, v17
	v_exp_f32_e32 v12, v12
	v_exp_f32_e32 v13, v13
	v_mul_f32_e32 v14, v4, v17
	v_mul_f32_e32 v15, v5, v17
	v_add_f32_e32 v12, 1.0, v12
	v_add_f32_e32 v13, 1.0, v13
	v_rcp_f32_e32 v12, v12
	v_rcp_f32_e32 v13, v13
	v_exp_f32_e32 v14, v14
	v_exp_f32_e32 v15, v15
	v_mul_f32_e32 v6, v6, v17
	v_mul_f32_e32 v7, v7, v17
	v_exp_f32_e32 v6, v6
	v_exp_f32_e32 v7, v7
	v_exp_f32_e32 v19, v16
	v_mul_f32_e32 v16, v75, v75
	v_pk_mul_f32 v[10:11], v[10:11], v[16:17] op_sel_hi:[1,0]
	v_add_f32_e32 v4, 1.0, v6
	v_pk_mul_f32 v[10:11], v[10:11], v[12:13]
	v_add_f32_e32 v12, 1.0, v14
	v_add_f32_e32 v13, 1.0, v15
	v_rcp_f32_e32 v12, v12
	v_rcp_f32_e32 v13, v13
	v_add_f32_e32 v5, 1.0, v7
	v_add_f32_e32 v18, 1.0, v18
	v_add_f32_e32 v19, 1.0, v19
	v_rcp_f32_e32 v4, v4
	v_rcp_f32_e32 v5, v5
	v_rcp_f32_e32 v18, v18
	v_rcp_f32_e32 v19, v19
	v_pk_mul_f32 v[0:1], v[0:1], v[16:17] op_sel_hi:[1,0]
	v_pk_mul_f32 v[8:9], v[8:9], v[16:17] op_sel_hi:[1,0]
	v_pk_mul_f32 v[6:7], v[0:1], v[12:13]
	v_pk_mul_f32 v[0:1], v[2:3], v[16:17] op_sel_hi:[1,0]
	v_pk_mul_f32 v[8:9], v[8:9], v[18:19]
	v_pk_mul_f32 v[4:5], v[0:1], v[4:5]
	v_cvt_pk_bf16_f32 v0, v8, v9
	v_cvt_pk_bf16_f32 v3, v4, v5
	v_mad_i64_i32 v[4:5], s[4:5], v64, s58, v[56:57]
	v_cvt_pk_bf16_f32 v1, v10, v11
	v_cvt_pk_bf16_f32 v2, v6, v7
	v_lshl_add_u64 v[4:5], v[4:5], 0, v[142:143]
	global_store_dwordx4 v[4:5], v[0:3], off
	s_branch .LBB0_885

; #define PG8_STAGE(bufoff, gbase, voff) do { _Pragma("unroll") for (int _i = 0; _i < 2; ++_i) \
;     __builtin_amdgcn_global_load_lds((const unsigned*)((const char*)(gbase) + (voff)[_i]), (PG8_LAS unsigned*)(lds + (bufoff) + ldsw + _i * 8192), 16, 0, 0); } while (0)
; #define PG8_LDA(dst, b, h) do { _Pragma("unroll") for (int m = 0; m < 4; ++m) _Pragma("unroll") for (int k = 0; k < 2; ++k) dst[m][k] = *(const PG8_LAS bf16x8*)(lds + PG8_SA(b, h) + aoff + m * 2048 + k * 1024); } while (0)
; #define PG8_LDB(dst, b, h) do { _Pragma("unroll") for (int n = 0; n < 2; ++n) _Pragma("unroll") for (int k = 0; k < 2; ++k) dst[n][k] = *(const PG8_LAS bf16x8*)(lds + PG8_SB(b, h) + boff + n * 2048 + k * 1024); } while (0)
; #define PG8_MMA(ai, bj, At, Bt) do { __builtin_amdgcn_s_setprio(1); _Pragma("unroll") for (int m = 0; m < 4; ++m) _Pragma("unroll") for (int n = 0; n < 2; ++n) _Pragma("unroll") for (int k = 0; k < 2; ++k) \
;     acc[ai][bj][m][n] = __builtin_amdgcn_mfma_f32_16x16x32_bf16(Bt[n][k], At[m][k], acc[ai][bj][m][n], 0, 0, 0); __builtin_amdgcn_s_setprio(0); } while (0)
; #define PG8_WAIT_V(n) asm volatile("s_waitcnt vmcnt(" #n ")" ::: "memory")
; #define PG8_WAIT_L(n) asm volatile("s_waitcnt lgkmcnt(" #n ")" ::: "memory")
; #define PG8_BAR __builtin_amdgcn_s_barrier()
; #define PG8_SCHED __builtin_amdgcn_sched_barrier(0)
; template <class Epi>
; DI void gemm_phase(PG8_LAS unsigned char* lds, const Gemm g, const StaticOrder& S, const Epi& E, const int wv) {
;     ...
;     for (int t = 0; t < nt; t += 2) {
;       const bool last = (t == nt - 2);
;       const char* a1 = cA + (size_t)(t + 1) * kstep;
;       const char* a2 = last ? nA : cA + (size_t)(t + 2) * kstep; const char* b2 = last ? nB : cB + (size_t)(t + 2) * kstep;
;       const char* a3 = a2 + kstep; const char* b3 = b2 + kstep;
;       PG8_LDB(B0, 0, 0); PG8_SCHED; PG8_LDA(At, 0, 0); PG8_STAGE(PG8_SA(1, 1), a1 + hstep, voffA);
;       PG8_WAIT_L(8); PG8_BAR; PG8_WAIT_L(0); PG8_MMA(0, 0, At, B0); PG8_BAR; PG8_SCHED;
;       PG8_LDB(B1, 0, 1); PG8_STAGE(PG8_SB(0, 0), b2, voffB);
;       PG8_BAR; PG8_WAIT_L(0); PG8_MMA(0, 1, At, B1); PG8_BAR;
;       PG8_LDA(At, 0, 1); PG8_STAGE(PG8_SA(0, 0), a2, voffA);
;       PG8_BAR; PG8_WAIT_L(0); PG8_MMA(1, 0, At, B0); PG8_BAR; PG8_SCHED;
;       PG8_STAGE(PG8_SB(0, 1), b2 + hstep, voffB);
;       PG8_WAIT_V(6); PG8_BAR; PG8_MMA(1, 1, At, B1); PG8_BAR;
.LBB0_1367:
	ds_read_b128 v[142:145], v155
	ds_read_b128 v[146:149], v155 offset:1024
	ds_read_b128 v[160:163], v155 offset:2048
	ds_read_b128 v[164:167], v155 offset:3072
	s_add_u32 s8, s6, 0xfffc0080
	s_addc_u32 s9, s7, -1
	s_cmp_eq_u32 s61, 12
	s_cselect_b32 s35, s5, s9
	s_cselect_b32 s34, s25, s8
	s_cselect_b32 s9, s23, s60
	s_cselect_b32 s8, s58, s59
	v_lshl_add_u64 v[150:151], s[6:7], 0, v[136:137]
	s_add_i32 m0, s31, 0xc000
	ds_read_b128 v[168:171], v156
	ds_read_b128 v[172:175], v156 offset:1024
	ds_read_b128 v[176:179], v156 offset:2048
	ds_read_b128 v[180:183], v156 offset:3072
	ds_read_b128 v[184:187], v156 offset:4096
	ds_read_b128 v[188:191], v156 offset:5120
	ds_read_b128 v[192:195], v156 offset:6144
	ds_read_b128 v[196:199], v156 offset:7168
	global_load_lds_dwordx4 v[150:151], off
	v_lshl_add_u64 v[150:151], s[6:7], 0, v[138:139]
	s_add_i32 m0, s31, 0xe000
	s_nop 0
	global_load_lds_dwordx4 v[150:151], off
	s_waitcnt lgkmcnt(8)
	s_barrier
	s_waitcnt lgkmcnt(0)
	s_setprio 1
	s_waitcnt lgkmcnt(0)
	v_mfma_f32_16x16x32_bf16 v[116:119], v[142:145], v[168:171], v[116:119]
	v_mfma_f32_16x16x32_bf16 v[112:115], v[160:163], v[168:171], v[112:115]
	v_mfma_f32_16x16x32_bf16 v[108:111], v[142:145], v[176:179], v[108:111]
	v_mfma_f32_16x16x32_bf16 v[100:103], v[160:163], v[176:179], v[100:103]
	v_mfma_f32_16x16x32_bf16 v[92:95], v[142:145], v[184:187], v[92:95]
	v_mfma_f32_16x16x32_bf16 v[84:87], v[160:163], v[184:187], v[84:87]
	v_mfma_f32_16x16x32_bf16 v[76:79], v[142:145], v[192:195], v[76:79]
	v_mfma_f32_16x16x32_bf16 v[68:71], v[160:163], v[192:195], v[68:71]
	v_mfma_f32_16x16x32_bf16 v[116:119], v[146:149], v[172:175], v[116:119]
	v_mfma_f32_16x16x32_bf16 v[112:115], v[164:167], v[172:175], v[112:115]
	v_mfma_f32_16x16x32_bf16 v[108:111], v[146:149], v[180:183], v[108:111]
	v_mfma_f32_16x16x32_bf16 v[100:103], v[164:167], v[180:183], v[100:103]
	v_mfma_f32_16x16x32_bf16 v[92:95], v[146:149], v[188:191], v[92:95]
	v_mfma_f32_16x16x32_bf16 v[84:87], v[164:167], v[188:191], v[84:87]
	v_mfma_f32_16x16x32_bf16 v[76:79], v[146:149], v[196:199], v[76:79]
	v_mfma_f32_16x16x32_bf16 v[68:71], v[164:167], v[196:199], v[68:71]
	s_setprio 0
	s_barrier
	s_add_i32 s62, s53, s42
	v_lshl_add_u64 v[150:151], s[8:9], 0, v[132:133]
	s_mov_b32 m0, s62
	ds_read_b128 v[200:203], v157
	ds_read_b128 v[204:207], v157 offset:1024
	ds_read_b128 v[208:211], v157 offset:2048
	ds_read_b128 v[212:215], v157 offset:3072
	global_load_lds_dwordx4 v[150:151], off
	v_lshl_add_u64 v[216:217], s[8:9], 0, v[128:129]
	s_add_i32 m0, s62, 0x2000
	s_nop 0
	global_load_lds_dwordx4 v[216:217], off
	s_barrier
	s_waitcnt lgkmcnt(0)
	s_setprio 1
	s_waitcnt lgkmcnt(0)
	v_mfma_f32_16x16x32_bf16 v[124:127], v[200:203], v[168:171], v[124:127]
	v_mfma_f32_16x16x32_bf16 v[120:123], v[208:211], v[168:171], v[120:123]
	v_mfma_f32_16x16x32_bf16 v[104:107], v[200:203], v[176:179], v[104:107]
	v_mfma_f32_16x16x32_bf16 v[96:99], v[208:211], v[176:179], v[96:99]
	v_mfma_f32_16x16x32_bf16 v[88:91], v[200:203], v[184:187], v[88:91]
	v_mfma_f32_16x16x32_bf16 v[80:83], v[208:211], v[184:187], v[80:83]
	v_mfma_f32_16x16x32_bf16 v[72:75], v[200:203], v[192:195], v[72:75]
	v_mfma_f32_16x16x32_bf16 v[64:67], v[208:211], v[192:195], v[64:67]
	v_mfma_f32_16x16x32_bf16 v[124:127], v[204:207], v[172:175], v[124:127]
	v_mfma_f32_16x16x32_bf16 v[120:123], v[212:215], v[172:175], v[120:123]
	v_mfma_f32_16x16x32_bf16 v[104:107], v[204:207], v[180:183], v[104:107]
	v_mfma_f32_16x16x32_bf16 v[96:99], v[212:215], v[180:183], v[96:99]
	v_mfma_f32_16x16x32_bf16 v[88:91], v[204:207], v[188:191], v[88:91]
	v_mfma_f32_16x16x32_bf16 v[80:83], v[212:215], v[188:191], v[80:83]
	v_mfma_f32_16x16x32_bf16 v[72:75], v[204:207], v[196:199], v[72:75]
	v_mfma_f32_16x16x32_bf16 v[64:67], v[212:215], v[196:199], v[64:67]
	s_setprio 0
	s_mov_b32 m0, s31
	v_lshl_add_u64 v[218:219], s[34:35], 0, v[134:135]
	s_barrier
	ds_read_b128 v[168:171], v156 offset:16384
	ds_read_b128 v[172:175], v156 offset:17408
	ds_read_b128 v[176:179], v156 offset:18432
	ds_read_b128 v[180:183], v156 offset:19456
	ds_read_b128 v[184:187], v156 offset:20480
	ds_read_b128 v[188:191], v156 offset:21504
	ds_read_b128 v[192:195], v156 offset:22528
	ds_read_b128 v[196:199], v156 offset:23552
	global_load_lds_dwordx4 v[218:219], off
	v_lshl_add_u64 v[220:221], s[34:35], 0, v[130:131]
	s_mov_b32 m0, s45
	s_nop 0
	global_load_lds_dwordx4 v[220:221], off
	s_barrier
	s_waitcnt lgkmcnt(0)
	s_setprio 1
	s_waitcnt lgkmcnt(0)
	v_mfma_f32_16x16x32_bf16 v[52:55], v[142:145], v[168:171], v[52:55]
	v_mfma_f32_16x16x32_bf16 v[48:51], v[160:163], v[168:171], v[48:51]
	v_mfma_f32_16x16x32_bf16 v[44:47], v[142:145], v[176:179], v[44:47]
	v_mfma_f32_16x16x32_bf16 v[36:39], v[160:163], v[176:179], v[36:39]
	v_mfma_f32_16x16x32_bf16 v[28:31], v[142:145], v[184:187], v[28:31]
	v_mfma_f32_16x16x32_bf16 v[20:23], v[160:163], v[184:187], v[20:23]
	v_mfma_f32_16x16x32_bf16 v[12:15], v[142:145], v[192:195], v[12:15]
	v_mfma_f32_16x16x32_bf16 v[4:7], v[160:163], v[192:195], v[4:7]
	v_mfma_f32_16x16x32_bf16 v[52:55], v[146:149], v[172:175], v[52:55]
	v_mfma_f32_16x16x32_bf16 v[48:51], v[164:167], v[172:175], v[48:51]
	v_mfma_f32_16x16x32_bf16 v[44:47], v[146:149], v[180:183], v[44:47]
	v_mfma_f32_16x16x32_bf16 v[36:39], v[164:167], v[180:183], v[36:39]
	v_mfma_f32_16x16x32_bf16 v[28:31], v[146:149], v[188:191], v[28:31]
	v_mfma_f32_16x16x32_bf16 v[20:23], v[164:167], v[188:191], v[20:23]
	v_mfma_f32_16x16x32_bf16 v[12:15], v[146:149], v[196:199], v[12:15]
	v_mfma_f32_16x16x32_bf16 v[4:7], v[164:167], v[196:199], v[4:7]
	s_setprio 0
	s_barrier
; #define PG8_STAGE(bufoff, gbase, voff) do { _Pragma("unroll") for (int _i = 0; _i < 2; ++_i) \
;     __builtin_amdgcn_global_load_lds((const unsigned*)((const char*)(gbase) + (voff)[_i]), (PG8_LAS unsigned*)(lds + (bufoff) + ldsw + _i * 8192), 16, 0, 0); } while (0)
; #define PG8_LDA(dst, b, h) do { _Pragma("unroll") for (int m = 0; m < 4; ++m) _Pragma("unroll") for (int k = 0; k < 2; ++k) dst[m][k] = *(const PG8_LAS bf16x8*)(lds + PG8_SA(b, h) + aoff + m * 2048 + k * 1024); } while (0)
; #define PG8_LDB(dst, b, h) do { _Pragma("unroll") for (int n = 0; n < 2; ++n) _Pragma("unroll") for (int k = 0; k < 2; ++k) dst[n][k] = *(const PG8_LAS bf16x8*)(lds + PG8_SB(b, h) + boff + n * 2048 + k * 1024); } while (0)
; #define PG8_MMA(ai, bj, At, Bt) do { __builtin_amdgcn_s_setprio(1); _Pragma("unroll") for (int m = 0; m < 4; ++m) _Pragma("unroll") for (int n = 0; n < 2; ++n) _Pragma("unroll") for (int k = 0; k < 2; ++k) \
;     acc[ai][bj][m][n] = __builtin_amdgcn_mfma_f32_16x16x32_bf16(Bt[n][k], At[m][k], acc[ai][bj][m][n], 0, 0, 0); __builtin_amdgcn_s_setprio(0); } while (0)
; #define PG8_WAIT_V(n) asm volatile("s_waitcnt vmcnt(" #n ")" ::: "memory")
; #define PG8_WAIT_L(n) asm volatile("s_waitcnt lgkmcnt(" #n ")" ::: "memory")
; #define PG8_BAR __builtin_amdgcn_s_barrier()
; #define PG8_SCHED __builtin_amdgcn_sched_barrier(0)
; template <class Epi>
; DI void gemm_phase(PG8_LAS unsigned char* lds, const Gemm g, const StaticOrder& S, const Epi& E, const int wv) {
;     ...
;       PG8_LDA(At, 0, 1); PG8_STAGE(PG8_SA(0, 0), a2, voffA);
;       PG8_BAR; PG8_WAIT_L(0); PG8_MMA(1, 0, At, B0); PG8_BAR; PG8_SCHED;
;       PG8_STAGE(PG8_SB(0, 1), b2 + hstep, voffB);
;       PG8_WAIT_V(6); PG8_BAR; PG8_MMA(1, 1, At, B1); PG8_BAR;
;       PG8_LDB(B0, 1, 0); PG8_SCHED; PG8_LDA(At, 1, 0); PG8_STAGE(PG8_SA(0, 1), a2 + hstep, voffA);
;       PG8_WAIT_L(8); PG8_BAR; PG8_WAIT_L(0); PG8_MMA(0, 0, At, B0); PG8_BAR; PG8_SCHED;
;       PG8_LDB(B1, 1, 1); PG8_STAGE(PG8_SB(1, 0), b3, voffB);
;       PG8_BAR; PG8_WAIT_L(0); PG8_MMA(0, 1, At, B1); PG8_BAR;
;       PG8_LDA(At, 1, 1); PG8_STAGE(PG8_SA(1, 0), a3, voffA);
;       PG8_BAR; PG8_WAIT_L(0); PG8_MMA(1, 0, At, B0); PG8_BAR; PG8_SCHED;
	s_add_u32 s62, s8, 0x40000
	s_addc_u32 s63, s9, 0
	s_add_i32 s64, s54, s42
	v_lshl_add_u64 v[142:143], s[62:63], 0, v[132:133]
	s_mov_b32 m0, s64
	s_nop 0
	global_load_lds_dwordx4 v[142:143], off
	v_lshl_add_u64 v[142:143], s[62:63], 0, v[128:129]
	s_add_i32 m0, s64, 0x2000
	s_nop 0
	global_load_lds_dwordx4 v[142:143], off
	s_waitcnt vmcnt(6)
	s_barrier
	s_setprio 1
	v_mfma_f32_16x16x32_bf16 v[60:63], v[200:203], v[168:171], v[60:63]
	v_mfma_f32_16x16x32_bf16 v[56:59], v[208:211], v[168:171], v[56:59]
	v_mfma_f32_16x16x32_bf16 v[40:43], v[200:203], v[176:179], v[40:43]
	v_mfma_f32_16x16x32_bf16 v[32:35], v[208:211], v[176:179], v[32:35]
	v_mfma_f32_16x16x32_bf16 v[24:27], v[200:203], v[184:187], v[24:27]
	v_mfma_f32_16x16x32_bf16 v[16:19], v[208:211], v[184:187], v[16:19]
	v_mfma_f32_16x16x32_bf16 v[8:11], v[200:203], v[192:195], v[8:11]
	v_mfma_f32_16x16x32_bf16 v[0:3], v[208:211], v[192:195], v[0:3]
	v_mfma_f32_16x16x32_bf16 v[60:63], v[204:207], v[172:175], v[60:63]
	v_mfma_f32_16x16x32_bf16 v[56:59], v[212:215], v[172:175], v[56:59]
	v_mfma_f32_16x16x32_bf16 v[40:43], v[204:207], v[180:183], v[40:43]
	v_mfma_f32_16x16x32_bf16 v[32:35], v[212:215], v[180:183], v[32:35]
	v_mfma_f32_16x16x32_bf16 v[24:27], v[204:207], v[188:191], v[24:27]
	v_mfma_f32_16x16x32_bf16 v[16:19], v[212:215], v[188:191], v[16:19]
	v_mfma_f32_16x16x32_bf16 v[8:11], v[204:207], v[196:199], v[8:11]
	v_mfma_f32_16x16x32_bf16 v[0:3], v[212:215], v[196:199], v[0:3]
	s_setprio 0
	s_add_i32 s62, 0, 0x18000
	v_add_u32_e32 v159, s62, v153
	s_barrier
	ds_read_b128 v[142:145], v159
	ds_read_b128 v[146:149], v159 offset:1024
	ds_read_b128 v[160:163], v159 offset:2048
	ds_read_b128 v[164:167], v159 offset:3072
	s_add_u32 s34, s34, 0x40000
	s_addc_u32 s35, s35, 0
	s_mov_b32 m0, s46
	v_lshl_add_u64 v[200:201], s[34:35], 0, v[134:135]
	ds_read_b128 v[168:171], v156 offset:32768
	ds_read_b128 v[172:175], v156 offset:33792
	ds_read_b128 v[176:179], v156 offset:34816
	ds_read_b128 v[180:183], v156 offset:35840
	ds_read_b128 v[184:187], v156 offset:36864
	ds_read_b128 v[188:191], v156 offset:37888
	ds_read_b128 v[192:195], v156 offset:38912
	ds_read_b128 v[196:199], v156 offset:39936
	global_load_lds_dwordx4 v[200:201], off
	v_lshl_add_u64 v[200:201], s[34:35], 0, v[130:131]
	s_mov_b32 m0, s47
	s_nop 0
	global_load_lds_dwordx4 v[200:201], off
	s_waitcnt lgkmcnt(8)
	s_barrier
	s_waitcnt lgkmcnt(0)
	s_setprio 1
	s_waitcnt lgkmcnt(0)
	v_mfma_f32_16x16x32_bf16 v[116:119], v[142:145], v[168:171], v[116:119]
	v_mfma_f32_16x16x32_bf16 v[112:115], v[160:163], v[168:171], v[112:115]
	v_mfma_f32_16x16x32_bf16 v[108:111], v[142:145], v[176:179], v[108:111]
	v_mfma_f32_16x16x32_bf16 v[100:103], v[160:163], v[176:179], v[100:103]
	v_mfma_f32_16x16x32_bf16 v[92:95], v[142:145], v[184:187], v[92:95]
	v_mfma_f32_16x16x32_bf16 v[84:87], v[160:163], v[184:187], v[84:87]
	v_mfma_f32_16x16x32_bf16 v[76:79], v[142:145], v[192:195], v[76:79]
	v_mfma_f32_16x16x32_bf16 v[68:71], v[160:163], v[192:195], v[68:71]
	v_mfma_f32_16x16x32_bf16 v[116:119], v[146:149], v[172:175], v[116:119]
	v_mfma_f32_16x16x32_bf16 v[112:115], v[164:167], v[172:175], v[112:115]
	v_mfma_f32_16x16x32_bf16 v[108:111], v[146:149], v[180:183], v[108:111]
	v_mfma_f32_16x16x32_bf16 v[100:103], v[164:167], v[180:183], v[100:103]
	v_mfma_f32_16x16x32_bf16 v[92:95], v[146:149], v[188:191], v[92:95]
	v_mfma_f32_16x16x32_bf16 v[84:87], v[164:167], v[188:191], v[84:87]
	v_mfma_f32_16x16x32_bf16 v[76:79], v[146:149], v[196:199], v[76:79]
	v_mfma_f32_16x16x32_bf16 v[68:71], v[164:167], v[196:199], v[68:71]
	s_setprio 0
	s_barrier
	s_add_i32 s34, 0, 0x1c000
	s_add_i32 s35, s62, s42
	v_add_u32_e32 v159, s34, v153
	v_lshl_add_u64 v[150:151], v[150:151], 0, s[18:19]
	s_mov_b32 m0, s35
	ds_read_b128 v[200:203], v159
	ds_read_b128 v[204:207], v159 offset:1024
	ds_read_b128 v[208:211], v159 offset:2048
	ds_read_b128 v[212:215], v159 offset:3072
	global_load_lds_dwordx4 v[150:151], off
	v_lshl_add_u64 v[150:151], v[216:217], 0, s[18:19]
	s_add_i32 m0, s35, 0x2000
	s_nop 0
	global_load_lds_dwordx4 v[150:151], off
	s_barrier
	s_waitcnt lgkmcnt(0)
	s_setprio 1
	s_waitcnt lgkmcnt(0)
	v_mfma_f32_16x16x32_bf16 v[124:127], v[200:203], v[168:171], v[124:127]
	v_mfma_f32_16x16x32_bf16 v[120:123], v[208:211], v[168:171], v[120:123]
	v_mfma_f32_16x16x32_bf16 v[104:107], v[200:203], v[176:179], v[104:107]
	v_mfma_f32_16x16x32_bf16 v[96:99], v[208:211], v[176:179], v[96:99]
	v_mfma_f32_16x16x32_bf16 v[88:91], v[200:203], v[184:187], v[88:91]
	v_mfma_f32_16x16x32_bf16 v[80:83], v[208:211], v[184:187], v[80:83]
	v_mfma_f32_16x16x32_bf16 v[72:75], v[200:203], v[192:195], v[72:75]
	v_mfma_f32_16x16x32_bf16 v[64:67], v[208:211], v[192:195], v[64:67]
	v_mfma_f32_16x16x32_bf16 v[124:127], v[204:207], v[172:175], v[124:127]
	v_mfma_f32_16x16x32_bf16 v[120:123], v[212:215], v[172:175], v[120:123]
	v_mfma_f32_16x16x32_bf16 v[104:107], v[204:207], v[180:183], v[104:107]
	v_mfma_f32_16x16x32_bf16 v[96:99], v[212:215], v[180:183], v[96:99]
	v_mfma_f32_16x16x32_bf16 v[88:91], v[204:207], v[188:191], v[88:91]
	v_mfma_f32_16x16x32_bf16 v[80:83], v[212:215], v[188:191], v[80:83]
	v_mfma_f32_16x16x32_bf16 v[72:75], v[204:207], v[196:199], v[72:75]
	v_mfma_f32_16x16x32_bf16 v[64:67], v[212:215], v[196:199], v[64:67]
	s_setprio 0
	s_mov_b32 m0, s49
	v_lshl_add_u64 v[150:151], v[218:219], 0, s[18:19]
	s_barrier
	ds_read_b128 v[168:171], v156 offset:49152
	ds_read_b128 v[172:175], v156 offset:50176
	ds_read_b128 v[176:179], v156 offset:51200
	ds_read_b128 v[180:183], v156 offset:52224
	ds_read_b128 v[184:187], v156 offset:53248
	ds_read_b128 v[188:191], v156 offset:54272
	ds_read_b128 v[192:195], v156 offset:55296
	ds_read_b128 v[196:199], v156 offset:56320
	global_load_lds_dwordx4 v[150:151], off
	v_lshl_add_u64 v[150:151], v[220:221], 0, s[18:19]
	s_mov_b32 m0, s50
	s_nop 0
	global_load_lds_dwordx4 v[150:151], off
	s_barrier
; #define PG8_STAGE(bufoff, gbase, voff) do { _Pragma("unroll") for (int _i = 0; _i < 2; ++_i) \
;     __builtin_amdgcn_global_load_lds((const unsigned*)((const char*)(gbase) + (voff)[_i]), (PG8_LAS unsigned*)(lds + (bufoff) + ldsw + _i * 8192), 16, 0, 0); } while (0)
; #define PG8_MMA(ai, bj, At, Bt) do { __builtin_amdgcn_s_setprio(1); _Pragma("unroll") for (int m = 0; m < 4; ++m) _Pragma("unroll") for (int n = 0; n < 2; ++n) _Pragma("unroll") for (int k = 0; k < 2; ++k) \
;     acc[ai][bj][m][n] = __builtin_amdgcn_mfma_f32_16x16x32_bf16(Bt[n][k], At[m][k], acc[ai][bj][m][n], 0, 0, 0); __builtin_amdgcn_s_setprio(0); } while (0)
; #define PG8_WAIT_V(n) asm volatile("s_waitcnt vmcnt(" #n ")" ::: "memory")
; #define PG8_WAIT_L(n) asm volatile("s_waitcnt lgkmcnt(" #n ")" ::: "memory")
; #define PG8_BAR __builtin_amdgcn_s_barrier()
; #define PG8_SCHED __builtin_amdgcn_sched_barrier(0)
; #define EPI_ROWS_BEGIN() \
;   _Pragma("unroll") for (int ai = 0; ai < 2; ++ai) { if (u.pm * 256 + ai * 128 >= T) continue;
; template <class Epi>
; DI void gemm_phase(PG8_LAS unsigned char* lds, const Gemm g, const StaticOrder& S, const Epi& E, const int wv) {
;     ...
;       PG8_BAR; PG8_WAIT_L(0); PG8_MMA(1, 0, At, B0); PG8_BAR; PG8_SCHED;
;       PG8_STAGE(PG8_SB(1, 1), b3 + hstep, voffB);
;       PG8_WAIT_V(6); PG8_BAR; PG8_MMA(1, 1, At, B1); PG8_BAR;
;   DI void operator()(AccRef acc, const pg8::Unit& u, int wr, int wc, int fr, int fq) const {
;     ...
;     EPI_ROWS_BEGIN()
;       float rs[4];
; #pragma unroll
;       for (int m = 0; m < 4; ++m) rs[m] = ss[row0 + ai * 128 + m * 16];
; #pragma unroll
;       for (int m = 0; m < 4; ++m) rs[m] = rsqrtf(rs[m] * (1.f / DM) + EPS);
; #pragma unroll
;       for (int m = 0; m < 4; ++m) {
;         const int row = row0 + ai * 128 + m * 16;
;         const float ne = rs[m] * -1.4426950408889634f, r2 = rs[m] * rs[m];
;         f32x4 y[2];
; #pragma unroll
;         for (int n = 0; n < 2; ++n)
; #pragma unroll
;           for (int e = 0; e < 4; ++e) {
;             const float a = acc[ai][0][m][n][e], b = acc[ai][1][m][n][e];
;             y[n][e] = a * b * r2 * __builtin_amdgcn_rcpf(1.f + __builtin_amdgcn_exp2f(a * ne));
	s_waitcnt lgkmcnt(0)
	s_setprio 1
	s_waitcnt lgkmcnt(0)
	v_mfma_f32_16x16x32_bf16 v[52:55], v[142:145], v[168:171], v[52:55]
	v_mfma_f32_16x16x32_bf16 v[48:51], v[160:163], v[168:171], v[48:51]
	v_mfma_f32_16x16x32_bf16 v[44:47], v[142:145], v[176:179], v[44:47]
	v_mfma_f32_16x16x32_bf16 v[36:39], v[160:163], v[176:179], v[36:39]
	v_mfma_f32_16x16x32_bf16 v[28:31], v[142:145], v[184:187], v[28:31]
	v_mfma_f32_16x16x32_bf16 v[20:23], v[160:163], v[184:187], v[20:23]
	v_mfma_f32_16x16x32_bf16 v[12:15], v[142:145], v[192:195], v[12:15]
	v_mfma_f32_16x16x32_bf16 v[4:7], v[160:163], v[192:195], v[4:7]
	v_mfma_f32_16x16x32_bf16 v[52:55], v[146:149], v[172:175], v[52:55]
	v_mfma_f32_16x16x32_bf16 v[48:51], v[164:167], v[172:175], v[48:51]
	v_mfma_f32_16x16x32_bf16 v[44:47], v[146:149], v[180:183], v[44:47]
	v_mfma_f32_16x16x32_bf16 v[36:39], v[164:167], v[180:183], v[36:39]
	v_mfma_f32_16x16x32_bf16 v[28:31], v[146:149], v[188:191], v[28:31]
	v_mfma_f32_16x16x32_bf16 v[20:23], v[164:167], v[188:191], v[20:23]
	v_mfma_f32_16x16x32_bf16 v[12:15], v[146:149], v[196:199], v[12:15]
	v_mfma_f32_16x16x32_bf16 v[4:7], v[164:167], v[196:199], v[4:7]
	s_setprio 0
	s_barrier
	s_add_u32 s8, s8, 0x40080
	s_addc_u32 s9, s9, 0
	s_add_i32 s34, s34, s42
	v_lshl_add_u64 v[142:143], s[8:9], 0, v[132:133]
	s_mov_b32 m0, s34
	s_nop 0
	global_load_lds_dwordx4 v[142:143], off
	v_lshl_add_u64 v[142:143], s[8:9], 0, v[128:129]
	s_add_i32 m0, s34, 0x2000
	s_nop 0
	global_load_lds_dwordx4 v[142:143], off
	s_waitcnt vmcnt(6)
	s_barrier
	s_setprio 1
	v_mfma_f32_16x16x32_bf16 v[60:63], v[200:203], v[168:171], v[60:63]
	v_mfma_f32_16x16x32_bf16 v[56:59], v[208:211], v[168:171], v[56:59]
	v_mfma_f32_16x16x32_bf16 v[40:43], v[200:203], v[176:179], v[40:43]
	v_mfma_f32_16x16x32_bf16 v[32:35], v[208:211], v[176:179], v[32:35]
	v_mfma_f32_16x16x32_bf16 v[24:27], v[200:203], v[184:187], v[24:27]
	v_mfma_f32_16x16x32_bf16 v[16:19], v[208:211], v[184:187], v[16:19]
	v_mfma_f32_16x16x32_bf16 v[8:11], v[200:203], v[192:195], v[8:11]
	v_mfma_f32_16x16x32_bf16 v[0:3], v[208:211], v[192:195], v[0:3]
	v_mfma_f32_16x16x32_bf16 v[60:63], v[204:207], v[172:175], v[60:63]
	v_mfma_f32_16x16x32_bf16 v[56:59], v[212:215], v[172:175], v[56:59]
	v_mfma_f32_16x16x32_bf16 v[40:43], v[204:207], v[180:183], v[40:43]
	v_mfma_f32_16x16x32_bf16 v[32:35], v[212:215], v[180:183], v[32:35]
	v_mfma_f32_16x16x32_bf16 v[24:27], v[204:207], v[188:191], v[24:27]
	v_mfma_f32_16x16x32_bf16 v[16:19], v[212:215], v[188:191], v[16:19]
	v_mfma_f32_16x16x32_bf16 v[8:11], v[204:207], v[196:199], v[8:11]
	v_mfma_f32_16x16x32_bf16 v[0:3], v[212:215], v[196:199], v[0:3]
	s_setprio 0
	s_add_i32 s61, s61, 2
	s_add_u32 s6, s6, 0x100
	s_addc_u32 s7, s7, 0
	s_add_u32 s59, s59, 0x100
	s_addc_u32 s60, s60, 0
	s_cmp_gt_u32 s61, 13
	s_barrier
	s_cbranch_scc0 .LBB0_1367
	v_lshl_or_b32 v142, s4, 7, v154
	v_ashrrev_i32_e32 v143, 31, v142
	v_lshl_add_u32 v144, s30, 8, v152
	s_cmpk_gt_i32 s30, 0x181
	v_lshlrev_b64 v[142:143], 1, v[142:143]
	s_cbranch_scc1 .LBB0_1370
	v_ashrrev_i32_e32 v145, 31, v144
	v_lshl_add_u64 v[146:147], v[144:145], 2, s[16:17]
	v_or_b32_e32 v150, 16, v144
	global_load_dword v145, v[146:147], off
	v_ashrrev_i32_e32 v151, 31, v150
	v_or_b32_e32 v148, 32, v144
	v_or_b32_e32 v146, 48, v144
	v_lshl_add_u64 v[160:161], v[150:151], 2, s[16:17]
	v_ashrrev_i32_e32 v149, 31, v148
	v_ashrrev_i32_e32 v147, 31, v146
	v_lshl_add_u64 v[162:163], v[148:149], 2, s[16:17]
	v_lshl_add_u64 v[164:165], v[146:147], 2, s[16:17]
	global_load_dword v147, v[160:161], off
	global_load_dword v149, v[162:163], off
	global_load_dword v151, v[164:165], off
	v_add_u32_e32 v224, 0x80, v144
	v_ashrrev_i32_e32 v225, 31, v224
	v_lshl_add_u64 v[226:227], v[224:225], 2, s[16:17]
	global_load_dword v250, v[226:227], off
	global_load_dword v251, v[226:227], off offset:64
	global_load_dword v252, v[226:227], off offset:128
	global_load_dword v253, v[226:227], off offset:192
	v_pk_mul_f32 v[160:161], v[112:113], v[120:121]
	v_mov_b64_e32 v[120:121], s[14:15]
	v_mad_i64_i32 v[162:163], s[4:5], v144, s57, v[120:121]
	v_pk_mul_f32 v[126:127], v[118:119], v[126:127]
	v_pk_mul_f32 v[124:125], v[116:117], v[124:125]
	v_pk_mul_f32 v[122:123], v[114:115], v[122:123]
	v_pk_mul_f32 v[104:105], v[108:109], v[104:105]
	v_pk_mul_f32 v[106:107], v[110:111], v[106:107]
	v_pk_mul_f32 v[98:99], v[102:103], v[98:99]
	v_lshl_add_u64 v[162:163], v[162:163], 0, v[142:143]
	v_pk_mul_f32 v[96:97], v[100:101], v[96:97]
	v_pk_mul_f32 v[88:89], v[92:93], v[88:89]
	v_pk_mul_f32 v[90:91], v[94:95], v[90:91]
	v_pk_mul_f32 v[82:83], v[86:87], v[82:83]
	v_pk_mul_f32 v[80:81], v[84:85], v[80:81]
	v_pk_mul_f32 v[72:73], v[76:77], v[72:73]
	v_pk_mul_f32 v[74:75], v[78:79], v[74:75]
	v_pk_mul_f32 v[66:67], v[70:71], v[66:67]
	v_pk_mul_f32 v[64:65], v[68:69], v[64:65]
	s_waitcnt vmcnt(4)
; DI u32x4 pack8v(f32x4 a, f32x4 b) { return u32x4{cvtpk(a[0], a[1]), cvtpk(a[2], a[3]), cvtpk(b[0], b[1]), cvtpk(b[2], b[3])}; }
;   DI void operator()(AccRef acc, const pg8::Unit& u, int wr, int wc, int fr, int fq) const {
;     ...
;       float rs[4];
; #pragma unroll
;       for (int m = 0; m < 4; ++m) rs[m] = ss[row0 + ai * 128 + m * 16];
; #pragma unroll
;       for (int m = 0; m < 4; ++m) rs[m] = rsqrtf(rs[m] * (1.f / DM) + EPS);
; #pragma unroll
;       for (int m = 0; m < 4; ++m) {
;         const int row = row0 + ai * 128 + m * 16;
;         const float ne = rs[m] * -1.4426950408889634f, r2 = rs[m] * rs[m];
;         f32x4 y[2];
; #pragma unroll
;         for (int n = 0; n < 2; ++n)
; #pragma unroll
;           for (int e = 0; e < 4; ++e) {
;             const float a = acc[ai][0][m][n][e], b = acc[ai][1][m][n][e];
;             y[n][e] = a * b * r2 * __builtin_amdgcn_rcpf(1.f + __builtin_amdgcn_exp2f(a * ne));
;           }
;         *(u32x4*)(act + (size_t)row * FFN + col0) = pack8v(y[0], y[1]);
	v_fmamk_f32 v145, v145, 0x3a800000, v158
	v_mul_f32_e32 v159, 0x4b800000, v145
	v_cmp_gt_f32_e32 vcc, s55, v145
	v_fmamk_f32 v147, v147, 0x3a800000, v158
	v_fmamk_f32 v149, v149, 0x3a800000, v158
	v_fmamk_f32 v151, v151, 0x3a800000, v158
	v_cndmask_b32_e32 v145, v145, v159, vcc
	v_mul_f32_e32 v159, 0x4b800000, v147
	v_cmp_gt_f32_e64 s[4:5], s55, v147
	v_mul_f32_e32 v164, 0x4b800000, v149
	v_mul_f32_e32 v165, 0x4b800000, v151
	v_rsq_f32_e32 v145, v145
	v_cndmask_b32_e64 v147, v147, v159, s[4:5]
	v_cmp_gt_f32_e64 s[6:7], s55, v149
	v_cmp_gt_f32_e64 s[8:9], s55, v151
	v_rsq_f32_e32 v147, v147
	v_cndmask_b32_e64 v149, v149, v164, s[6:7]
	v_cndmask_b32_e64 v151, v151, v165, s[8:9]
	v_rsq_f32_e32 v149, v149
	v_rsq_f32_e32 v151, v151
	v_mul_f32_e32 v159, 0x45800000, v145
	v_cndmask_b32_e32 v145, v145, v159, vcc
	v_mul_f32_e32 v159, 0x45800000, v147
	v_mul_f32_e32 v164, 0x45800000, v149
	v_mul_f32_e32 v165, 0x45800000, v151
	v_cndmask_b32_e64 v147, v147, v159, s[4:5]
	v_mul_f32_e32 v159, 0xbfb8aa3b, v145
	v_cndmask_b32_e64 v149, v149, v164, s[6:7]
	v_cndmask_b32_e64 v151, v151, v165, s[8:9]
	v_mul_f32_e32 v164, v145, v145
	v_mul_f32_e32 v165, v117, v159
	v_mul_f32_e32 v145, v116, v159
	v_pk_mul_f32 v[116:117], v[124:125], v[164:165] op_sel_hi:[1,0]
	v_mul_f32_e32 v124, v118, v159
	v_mul_f32_e32 v125, v119, v159
	v_pk_mul_f32 v[118:119], v[126:127], v[164:165] op_sel_hi:[1,0]
	v_mul_f32_e32 v126, v112, v159
	v_mul_f32_e32 v127, v113, v159
	v_pk_mul_f32 v[112:113], v[160:161], v[164:165] op_sel_hi:[1,0]
	v_mul_f32_e32 v160, v114, v159
	v_mul_f32_e32 v159, v115, v159
	v_pk_mul_f32 v[114:115], v[122:123], v[164:165] op_sel_hi:[1,0]
	v_mul_f32_e32 v123, 0xbfb8aa3b, v147
	v_mul_f32_e32 v161, v108, v123
	v_mul_f32_e32 v164, v109, v123
	v_mul_f32_e32 v108, v110, v123
	v_mul_f32_e32 v109, v111, v123
	v_mul_f32_e32 v122, v147, v147
	v_exp_f32_e32 v145, v145
	v_exp_f32_e32 v147, v165
	v_exp_f32_e32 v124, v124
	v_exp_f32_e32 v125, v125
	v_exp_f32_e32 v126, v126
	v_exp_f32_e32 v127, v127
	v_exp_f32_e32 v160, v160
	v_exp_f32_e32 v159, v159
	v_exp_f32_e32 v108, v108
	v_exp_f32_e32 v109, v109
	v_exp_f32_e32 v166, v161
	v_exp_f32_e32 v167, v164
	v_add_f32_e32 v145, 1.0, v145
	v_add_f32_e32 v147, 1.0, v147
	v_add_f32_e32 v161, 1.0, v124
	v_add_f32_e32 v164, 1.0, v125
	v_add_f32_e32 v165, 1.0, v126
	v_add_f32_e32 v168, 1.0, v127
	v_add_f32_e32 v169, 1.0, v160
	v_add_f32_e32 v159, 1.0, v159
	v_add_f32_e32 v108, 1.0, v108
	v_add_f32_e32 v109, 1.0, v109
	v_mul_f32_e32 v110, v100, v123
	v_mul_f32_e32 v111, v101, v123
	v_rcp_f32_e32 v124, v145
	v_rcp_f32_e32 v125, v147
	v_rcp_f32_e32 v126, v161
	v_rcp_f32_e32 v127, v164
	v_rcp_f32_e32 v160, v165
	v_rcp_f32_e32 v161, v168
	v_rcp_f32_e32 v164, v169
	v_rcp_f32_e32 v165, v159
	v_rcp_f32_e32 v108, v108
	v_rcp_f32_e32 v109, v109
	v_exp_f32_e32 v110, v110
	v_exp_f32_e32 v111, v111
	v_mul_f32_e32 v102, v102, v123
	v_mul_f32_e32 v103, v103, v123
	v_exp_f32_e32 v102, v102
	v_exp_f32_e32 v103, v103
	v_pk_mul_f32 v[106:107], v[106:107], v[122:123] op_sel_hi:[1,0]
	v_pk_mul_f32 v[116:117], v[116:117], v[124:125]
	v_pk_mul_f32 v[118:119], v[118:119], v[126:127]
	v_pk_mul_f32 v[124:125], v[112:113], v[160:161]
	v_pk_mul_f32 v[126:127], v[114:115], v[164:165]
	v_pk_mul_f32 v[106:107], v[106:107], v[108:109]
	v_add_f32_e32 v108, 1.0, v110
	v_add_f32_e32 v109, 1.0, v111
	v_cvt_pk_bf16_f32 v112, v116, v117
	v_cvt_pk_bf16_f32 v113, v118, v119
	v_cvt_pk_bf16_f32 v114, v124, v125
	v_cvt_pk_bf16_f32 v115, v126, v127
	v_rcp_f32_e32 v108, v108
	v_rcp_f32_e32 v109, v109
	v_add_f32_e32 v100, 1.0, v102
	v_add_f32_e32 v101, 1.0, v103
	v_add_f32_e32 v145, 1.0, v166
	global_store_dwordx4 v[162:163], v[112:115], off
	v_rcp_f32_e32 v100, v100
	v_rcp_f32_e32 v101, v101
	v_add_f32_e32 v113, 1.0, v167
	v_rcp_f32_e32 v112, v145
	v_rcp_f32_e32 v113, v113
	v_pk_mul_f32 v[96:97], v[96:97], v[122:123] op_sel_hi:[1,0]
	v_pk_mul_f32 v[104:105], v[104:105], v[122:123] op_sel_hi:[1,0]
	v_pk_mul_f32 v[102:103], v[96:97], v[108:109]
	v_pk_mul_f32 v[96:97], v[98:99], v[122:123] op_sel_hi:[1,0]
	v_pk_mul_f32 v[104:105], v[104:105], v[112:113]
	v_pk_mul_f32 v[100:101], v[96:97], v[100:101]
	v_cvt_pk_bf16_f32 v96, v104, v105
	v_cvt_pk_bf16_f32 v99, v100, v101
	v_mad_i64_i32 v[100:101], s[4:5], v150, s57, v[120:121]
	v_cvt_pk_bf16_f32 v97, v106, v107
	v_cvt_pk_bf16_f32 v98, v102, v103
	v_lshl_add_u64 v[100:101], v[100:101], 0, v[142:143]
	global_store_dwordx4 v[100:101], v[96:99], off
	s_nop 1
	v_mul_f32_e32 v97, 0xbfb8aa3b, v149
	v_mul_f32_e32 v96, v92, v97
	v_exp_f32_e32 v98, v96
	v_mul_f32_e32 v96, v93, v97
	v_mul_f32_e32 v92, v94, v97
	v_mul_f32_e32 v93, v95, v97
	v_exp_f32_e32 v92, v92
	v_exp_f32_e32 v93, v93
	v_mul_f32_e32 v94, v84, v97
	v_mul_f32_e32 v95, v85, v97
	v_add_f32_e32 v92, 1.0, v92
	v_add_f32_e32 v93, 1.0, v93
	v_rcp_f32_e32 v92, v92
	v_rcp_f32_e32 v93, v93
	v_exp_f32_e32 v94, v94
	v_exp_f32_e32 v95, v95
	v_mul_f32_e32 v86, v86, v97
	v_mul_f32_e32 v87, v87, v97
	v_exp_f32_e32 v86, v86
	v_exp_f32_e32 v87, v87
	v_exp_f32_e32 v99, v96
	v_mul_f32_e32 v96, v149, v149
	v_pk_mul_f32 v[90:91], v[90:91], v[96:97] op_sel_hi:[1,0]
	v_add_f32_e32 v84, 1.0, v86
	v_pk_mul_f32 v[90:91], v[90:91], v[92:93]
	v_add_f32_e32 v92, 1.0, v94
	v_add_f32_e32 v93, 1.0, v95
	v_rcp_f32_e32 v92, v92
	v_rcp_f32_e32 v93, v93
	v_add_f32_e32 v85, 1.0, v87
	v_add_f32_e32 v98, 1.0, v98
	v_add_f32_e32 v99, 1.0, v99
	v_rcp_f32_e32 v84, v84
	v_rcp_f32_e32 v85, v85
	v_rcp_f32_e32 v98, v98
	v_rcp_f32_e32 v99, v99
	v_pk_mul_f32 v[80:81], v[80:81], v[96:97] op_sel_hi:[1,0]
	v_pk_mul_f32 v[88:89], v[88:89], v[96:97] op_sel_hi:[1,0]
	v_pk_mul_f32 v[86:87], v[80:81], v[92:93]
; DI u32x4 pack8v(f32x4 a, f32x4 b) { return u32x4{cvtpk(a[0], a[1]), cvtpk(a[2], a[3]), cvtpk(b[0], b[1]), cvtpk(b[2], b[3])}; }
; #define EPI_ROWS_BEGIN() \
;   _Pragma("unroll") for (int ai = 0; ai < 2; ++ai) { if (u.pm * 256 + ai * 128 >= T) continue;
;   DI void operator()(AccRef acc, const pg8::Unit& u, int wr, int wc, int fr, int fq) const {
;     ...
;     EPI_ROWS_BEGIN()
;       float rs[4];
; #pragma unroll
;       for (int m = 0; m < 4; ++m) rs[m] = ss[row0 + ai * 128 + m * 16];
; #pragma unroll
;       for (int m = 0; m < 4; ++m) rs[m] = rsqrtf(rs[m] * (1.f / DM) + EPS);
; #pragma unroll
;       for (int m = 0; m < 4; ++m) {
;         const int row = row0 + ai * 128 + m * 16;
;         const float ne = rs[m] * -1.4426950408889634f, r2 = rs[m] * rs[m];
;         f32x4 y[2];
; #pragma unroll
;         for (int n = 0; n < 2; ++n)
; #pragma unroll
;           for (int e = 0; e < 4; ++e) {
;             const float a = acc[ai][0][m][n][e], b = acc[ai][1][m][n][e];
;             y[n][e] = a * b * r2 * __builtin_amdgcn_rcpf(1.f + __builtin_amdgcn_exp2f(a * ne));
;           }
;         *(u32x4*)(act + (size_t)row * FFN + col0) = pack8v(y[0], y[1]);
	v_pk_mul_f32 v[80:81], v[82:83], v[96:97] op_sel_hi:[1,0]
	v_pk_mul_f32 v[88:89], v[88:89], v[98:99]
	v_pk_mul_f32 v[84:85], v[80:81], v[84:85]
	v_cvt_pk_bf16_f32 v80, v88, v89
	v_cvt_pk_bf16_f32 v83, v84, v85
	v_mad_i64_i32 v[84:85], s[4:5], v148, s57, v[120:121]
	v_cvt_pk_bf16_f32 v81, v90, v91
	v_cvt_pk_bf16_f32 v82, v86, v87
	v_lshl_add_u64 v[84:85], v[84:85], 0, v[142:143]
	global_store_dwordx4 v[84:85], v[80:83], off
	s_nop 1
	v_mul_f32_e32 v81, 0xbfb8aa3b, v151
	v_mul_f32_e32 v80, v76, v81
	v_exp_f32_e32 v82, v80
	v_mul_f32_e32 v80, v77, v81
	v_mul_f32_e32 v76, v78, v81
	v_mul_f32_e32 v77, v79, v81
	v_exp_f32_e32 v76, v76
	v_exp_f32_e32 v77, v77
	v_mul_f32_e32 v78, v68, v81
	v_mul_f32_e32 v79, v69, v81
	v_add_f32_e32 v76, 1.0, v76
	v_add_f32_e32 v77, 1.0, v77
	v_rcp_f32_e32 v76, v76
	v_rcp_f32_e32 v77, v77
	v_exp_f32_e32 v78, v78
	v_exp_f32_e32 v79, v79
	v_mul_f32_e32 v70, v70, v81
	v_mul_f32_e32 v71, v71, v81
	v_exp_f32_e32 v70, v70
	v_exp_f32_e32 v71, v71
	v_exp_f32_e32 v83, v80
	v_mul_f32_e32 v80, v151, v151
	v_pk_mul_f32 v[74:75], v[74:75], v[80:81] op_sel_hi:[1,0]
	v_add_f32_e32 v68, 1.0, v70
	v_pk_mul_f32 v[74:75], v[74:75], v[76:77]
	v_add_f32_e32 v76, 1.0, v78
	v_add_f32_e32 v77, 1.0, v79
	v_rcp_f32_e32 v76, v76
	v_rcp_f32_e32 v77, v77
	v_add_f32_e32 v69, 1.0, v71
	v_add_f32_e32 v82, 1.0, v82
	v_add_f32_e32 v83, 1.0, v83
	v_rcp_f32_e32 v68, v68
	v_rcp_f32_e32 v69, v69
	v_rcp_f32_e32 v82, v82
	v_rcp_f32_e32 v83, v83
	v_pk_mul_f32 v[64:65], v[64:65], v[80:81] op_sel_hi:[1,0]
	v_pk_mul_f32 v[72:73], v[72:73], v[80:81] op_sel_hi:[1,0]
	v_pk_mul_f32 v[70:71], v[64:65], v[76:77]
	v_pk_mul_f32 v[64:65], v[66:67], v[80:81] op_sel_hi:[1,0]
	v_pk_mul_f32 v[72:73], v[72:73], v[82:83]
	v_pk_mul_f32 v[68:69], v[64:65], v[68:69]
	v_cvt_pk_bf16_f32 v64, v72, v73
	v_cvt_pk_bf16_f32 v67, v68, v69
	v_mad_i64_i32 v[68:69], s[4:5], v146, s57, v[120:121]
	v_cvt_pk_bf16_f32 v65, v74, v75
	v_cvt_pk_bf16_f32 v66, v70, v71
	v_lshl_add_u64 v[68:69], v[68:69], 0, v[142:143]
	global_store_dwordx4 v[68:69], v[64:67], off
.LBB0_1370:
	s_cmpk_gt_i32 s30, 0x180
	s_cbranch_scc1 .LBB0_1363
	v_add_u32_e32 v70, 0x80, v144
	v_ashrrev_i32_e32 v71, 31, v70
	v_add_u32_e32 v68, 0x90, v144
	v_add_u32_e32 v66, 0xa0, v144
	v_add_u32_e32 v64, 0xb0, v144
	v_lshl_add_u64 v[72:73], v[70:71], 2, s[16:17]
	v_ashrrev_i32_e32 v69, 31, v68
	v_ashrrev_i32_e32 v67, 31, v66
	v_ashrrev_i32_e32 v65, 31, v64
	v_lshl_add_u64 v[74:75], v[68:69], 2, s[16:17]
	v_lshl_add_u64 v[76:77], v[66:67], 2, s[16:17]
	v_lshl_add_u64 v[78:79], v[64:65], 2, s[16:17]
	v_pk_mul_f32 v[72:73], v[48:49], v[56:57]
	v_mov_b64_e32 v[56:57], s[14:15]
	v_mad_i64_i32 v[70:71], s[4:5], v70, s57, v[56:57]
	v_pk_mul_f32 v[62:63], v[54:55], v[62:63]
	v_pk_mul_f32 v[60:61], v[52:53], v[60:61]
	v_pk_mul_f32 v[58:59], v[50:51], v[58:59]
	v_pk_mul_f32 v[40:41], v[44:45], v[40:41]
	v_pk_mul_f32 v[42:43], v[46:47], v[42:43]
	v_pk_mul_f32 v[34:35], v[38:39], v[34:35]
	v_lshl_add_u64 v[70:71], v[70:71], 0, v[142:143]
	v_pk_mul_f32 v[32:33], v[36:37], v[32:33]
	v_pk_mul_f32 v[24:25], v[28:29], v[24:25]
	v_pk_mul_f32 v[26:27], v[30:31], v[26:27]
	v_pk_mul_f32 v[18:19], v[22:23], v[18:19]
	v_pk_mul_f32 v[16:17], v[20:21], v[16:17]
	v_pk_mul_f32 v[8:9], v[12:13], v[8:9]
	v_pk_mul_f32 v[10:11], v[14:15], v[10:11]
	v_pk_mul_f32 v[2:3], v[6:7], v[2:3]
	v_pk_mul_f32 v[0:1], v[4:5], v[0:1]
	s_waitcnt vmcnt(4)
	v_fmamk_f32 v65, v250, 0x3a800000, v158
	v_fmamk_f32 v67, v251, 0x3a800000, v158
	v_fmamk_f32 v69, v252, 0x3a800000, v158
	v_fmamk_f32 v74, v253, 0x3a800000, v158
	v_mul_f32_e32 v75, 0x4b800000, v65
	v_mul_f32_e32 v76, 0x4b800000, v67
	v_cmp_gt_f32_e32 vcc, s55, v65
	v_cmp_gt_f32_e64 s[4:5], s55, v67
	v_mul_f32_e32 v77, 0x4b800000, v69
	v_mul_f32_e32 v78, 0x4b800000, v74
	v_cndmask_b32_e32 v65, v65, v75, vcc
	v_cndmask_b32_e64 v67, v67, v76, s[4:5]
	v_cmp_gt_f32_e64 s[6:7], s55, v69
	v_cmp_gt_f32_e64 s[8:9], s55, v74
	v_rsq_f32_e32 v65, v65
	v_cndmask_b32_e64 v69, v69, v77, s[6:7]
	v_cndmask_b32_e64 v74, v74, v78, s[8:9]
	v_rsq_f32_e32 v67, v67
	v_rsq_f32_e32 v69, v69
	v_rsq_f32_e32 v74, v74
	v_mul_f32_e32 v75, 0x45800000, v65
	v_mul_f32_e32 v76, 0x45800000, v67
	v_mul_f32_e32 v77, 0x45800000, v69
	v_mul_f32_e32 v78, 0x45800000, v74
	v_cndmask_b32_e32 v65, v65, v75, vcc
	v_cndmask_b32_e64 v67, v67, v76, s[4:5]
	v_cndmask_b32_e64 v69, v69, v77, s[6:7]
	v_cndmask_b32_e64 v75, v74, v78, s[8:9]
	v_mul_f32_e32 v77, 0xbfb8aa3b, v65
	v_mul_f32_e32 v74, v65, v65
	v_mul_f32_e32 v65, 0xbfb8aa3b, v67
	v_mul_f32_e32 v76, v67, v67
	v_mul_f32_e32 v67, v52, v77
	v_mul_f32_e32 v78, v53, v77
	v_pk_mul_f32 v[52:53], v[60:61], v[74:75] op_sel_hi:[1,0]
	v_mul_f32_e32 v60, v54, v77
	v_mul_f32_e32 v61, v55, v77
	v_pk_mul_f32 v[54:55], v[62:63], v[74:75] op_sel_hi:[1,0]
	v_mul_f32_e32 v62, v48, v77
	v_mul_f32_e32 v63, v49, v77
	v_pk_mul_f32 v[48:49], v[72:73], v[74:75] op_sel_hi:[1,0]
	v_mul_f32_e32 v72, v50, v77
	v_mul_f32_e32 v73, v51, v77
	v_pk_mul_f32 v[50:51], v[58:59], v[74:75] op_sel_hi:[1,0]
	v_mul_f32_e32 v58, v44, v65
	v_mul_f32_e32 v59, v45, v65
	v_mul_f32_e32 v44, v46, v65
	v_mul_f32_e32 v45, v47, v65
	v_exp_f32_e32 v67, v67
	v_exp_f32_e32 v74, v78
	v_exp_f32_e32 v60, v60
	v_exp_f32_e32 v61, v61
	v_exp_f32_e32 v62, v62
	v_exp_f32_e32 v63, v63
	v_exp_f32_e32 v72, v72
	v_exp_f32_e32 v73, v73
	v_exp_f32_e32 v44, v44
	v_exp_f32_e32 v45, v45
; DI u32x4 pack8v(f32x4 a, f32x4 b) { return u32x4{cvtpk(a[0], a[1]), cvtpk(a[2], a[3]), cvtpk(b[0], b[1]), cvtpk(b[2], b[3])}; }
;   DI void operator()(AccRef acc, const pg8::Unit& u, int wr, int wc, int fr, int fq) const {
;     ...
; #pragma unroll
;       for (int m = 0; m < 4; ++m) {
;         const int row = row0 + ai * 128 + m * 16;
;         const float ne = rs[m] * -1.4426950408889634f, r2 = rs[m] * rs[m];
;         f32x4 y[2];
; #pragma unroll
;         for (int n = 0; n < 2; ++n)
; #pragma unroll
;           for (int e = 0; e < 4; ++e) {
;             const float a = acc[ai][0][m][n][e], b = acc[ai][1][m][n][e];
;             y[n][e] = a * b * r2 * __builtin_amdgcn_rcpf(1.f + __builtin_amdgcn_exp2f(a * ne));
;           }
;         *(u32x4*)(act + (size_t)row * FFN + col0) = pack8v(y[0], y[1]);
;       }
	v_exp_f32_e32 v58, v58
	v_exp_f32_e32 v77, v59
	v_add_f32_e32 v59, 1.0, v67
	v_add_f32_e32 v67, 1.0, v74
	v_add_f32_e32 v60, 1.0, v60
	v_add_f32_e32 v61, 1.0, v61
	v_add_f32_e32 v62, 1.0, v62
	v_add_f32_e32 v63, 1.0, v63
	v_add_f32_e32 v72, 1.0, v72
	v_add_f32_e32 v73, 1.0, v73
	v_add_f32_e32 v44, 1.0, v44
	v_add_f32_e32 v45, 1.0, v45
	v_mul_f32_e32 v46, v36, v65
	v_mul_f32_e32 v47, v37, v65
	v_add_f32_e32 v74, 1.0, v58
	v_rcp_f32_e32 v58, v59
	v_rcp_f32_e32 v59, v67
	v_rcp_f32_e32 v60, v60
	v_rcp_f32_e32 v61, v61
	v_rcp_f32_e32 v62, v62
	v_rcp_f32_e32 v63, v63
	v_rcp_f32_e32 v72, v72
	v_rcp_f32_e32 v73, v73
	v_rcp_f32_e32 v44, v44
	v_rcp_f32_e32 v45, v45
	v_exp_f32_e32 v46, v46
	v_exp_f32_e32 v47, v47
	v_mul_f32_e32 v38, v38, v65
	v_mul_f32_e32 v39, v39, v65
	v_exp_f32_e32 v38, v38
	v_exp_f32_e32 v39, v39
	v_pk_mul_f32 v[42:43], v[42:43], v[76:77] op_sel_hi:[1,0]
	v_pk_mul_f32 v[52:53], v[52:53], v[58:59]
	v_pk_mul_f32 v[54:55], v[54:55], v[60:61]
	v_pk_mul_f32 v[58:59], v[48:49], v[62:63]
	v_pk_mul_f32 v[60:61], v[50:51], v[72:73]
	v_pk_mul_f32 v[42:43], v[42:43], v[44:45]
	v_add_f32_e32 v44, 1.0, v46
	v_add_f32_e32 v45, 1.0, v47
	v_cvt_pk_bf16_f32 v48, v52, v53
	v_cvt_pk_bf16_f32 v49, v54, v55
	v_cvt_pk_bf16_f32 v50, v58, v59
	v_cvt_pk_bf16_f32 v51, v60, v61
	v_rcp_f32_e32 v44, v44
	v_rcp_f32_e32 v45, v45
	v_add_f32_e32 v36, 1.0, v38
	v_add_f32_e32 v37, 1.0, v39
	global_store_dwordx4 v[70:71], v[48:51], off
	v_rcp_f32_e32 v36, v36
	v_rcp_f32_e32 v37, v37
	v_add_f32_e32 v49, 1.0, v77
	v_rcp_f32_e32 v48, v74
	v_rcp_f32_e32 v49, v49
	v_pk_mul_f32 v[32:33], v[32:33], v[76:77] op_sel_hi:[1,0]
	v_pk_mul_f32 v[40:41], v[40:41], v[76:77] op_sel_hi:[1,0]
	v_pk_mul_f32 v[38:39], v[32:33], v[44:45]
	v_pk_mul_f32 v[32:33], v[34:35], v[76:77] op_sel_hi:[1,0]
	v_pk_mul_f32 v[40:41], v[40:41], v[48:49]
	v_pk_mul_f32 v[36:37], v[32:33], v[36:37]
	v_cvt_pk_bf16_f32 v32, v40, v41
	v_cvt_pk_bf16_f32 v35, v36, v37
	v_mad_i64_i32 v[36:37], s[4:5], v68, s57, v[56:57]
	v_cvt_pk_bf16_f32 v33, v42, v43
	v_cvt_pk_bf16_f32 v34, v38, v39
	v_lshl_add_u64 v[36:37], v[36:37], 0, v[142:143]
	global_store_dwordx4 v[36:37], v[32:35], off
	s_nop 1
	v_mul_f32_e32 v33, 0xbfb8aa3b, v69
	v_mul_f32_e32 v32, v28, v33
	v_exp_f32_e32 v34, v32
	v_mul_f32_e32 v32, v29, v33
	v_mul_f32_e32 v28, v30, v33
	v_mul_f32_e32 v29, v31, v33
	v_exp_f32_e32 v28, v28
	v_exp_f32_e32 v29, v29
	v_mul_f32_e32 v30, v20, v33
	v_mul_f32_e32 v31, v21, v33
	v_add_f32_e32 v28, 1.0, v28
	v_add_f32_e32 v29, 1.0, v29
	v_rcp_f32_e32 v28, v28
	v_rcp_f32_e32 v29, v29
	v_exp_f32_e32 v30, v30
	v_exp_f32_e32 v31, v31
	v_mul_f32_e32 v22, v22, v33
	v_mul_f32_e32 v23, v23, v33
	v_exp_f32_e32 v22, v22
	v_exp_f32_e32 v23, v23
	v_exp_f32_e32 v35, v32
	v_mul_f32_e32 v32, v69, v69
	v_pk_mul_f32 v[26:27], v[26:27], v[32:33] op_sel_hi:[1,0]
	v_add_f32_e32 v20, 1.0, v22
	v_pk_mul_f32 v[26:27], v[26:27], v[28:29]
	v_add_f32_e32 v28, 1.0, v30
	v_add_f32_e32 v29, 1.0, v31
	v_rcp_f32_e32 v28, v28
	v_rcp_f32_e32 v29, v29
	v_add_f32_e32 v21, 1.0, v23
	v_add_f32_e32 v34, 1.0, v34
	v_add_f32_e32 v35, 1.0, v35
	v_rcp_f32_e32 v20, v20
	v_rcp_f32_e32 v21, v21
	v_rcp_f32_e32 v34, v34
	v_rcp_f32_e32 v35, v35
	v_pk_mul_f32 v[16:17], v[16:17], v[32:33] op_sel_hi:[1,0]
	v_pk_mul_f32 v[24:25], v[24:25], v[32:33] op_sel_hi:[1,0]
	v_pk_mul_f32 v[22:23], v[16:17], v[28:29]
	v_pk_mul_f32 v[16:17], v[18:19], v[32:33] op_sel_hi:[1,0]
	v_pk_mul_f32 v[24:25], v[24:25], v[34:35]
	v_pk_mul_f32 v[20:21], v[16:17], v[20:21]
	v_cvt_pk_bf16_f32 v16, v24, v25
	v_cvt_pk_bf16_f32 v19, v20, v21
	v_mad_i64_i32 v[20:21], s[4:5], v66, s57, v[56:57]
	v_cvt_pk_bf16_f32 v17, v26, v27
	v_cvt_pk_bf16_f32 v18, v22, v23
	v_lshl_add_u64 v[20:21], v[20:21], 0, v[142:143]
	global_store_dwordx4 v[20:21], v[16:19], off
	s_nop 1
	v_mul_f32_e32 v17, 0xbfb8aa3b, v75
	v_mul_f32_e32 v16, v12, v17
	v_exp_f32_e32 v18, v16
	v_mul_f32_e32 v16, v13, v17
	v_mul_f32_e32 v12, v14, v17
	v_mul_f32_e32 v13, v15, v17
	v_exp_f32_e32 v12, v12
	v_exp_f32_e32 v13, v13
	v_mul_f32_e32 v14, v4, v17
	v_mul_f32_e32 v15, v5, v17
	v_add_f32_e32 v12, 1.0, v12
	v_add_f32_e32 v13, 1.0, v13
	v_rcp_f32_e32 v12, v12
	v_rcp_f32_e32 v13, v13
	v_exp_f32_e32 v14, v14
	v_exp_f32_e32 v15, v15
	v_mul_f32_e32 v6, v6, v17
	v_mul_f32_e32 v7, v7, v17
	v_exp_f32_e32 v6, v6
	v_exp_f32_e32 v7, v7
	v_exp_f32_e32 v19, v16
	v_mul_f32_e32 v16, v75, v75
	v_pk_mul_f32 v[10:11], v[10:11], v[16:17] op_sel_hi:[1,0]
	v_add_f32_e32 v4, 1.0, v6
	v_pk_mul_f32 v[10:11], v[10:11], v[12:13]
	v_add_f32_e32 v12, 1.0, v14
	v_add_f32_e32 v13, 1.0, v15
	v_rcp_f32_e32 v12, v12
	v_rcp_f32_e32 v13, v13
	v_add_f32_e32 v5, 1.0, v7
	v_add_f32_e32 v18, 1.0, v18
	v_add_f32_e32 v19, 1.0, v19
	v_rcp_f32_e32 v4, v4
	v_rcp_f32_e32 v5, v5
	v_rcp_f32_e32 v18, v18
	v_rcp_f32_e32 v19, v19
	v_pk_mul_f32 v[0:1], v[0:1], v[16:17] op_sel_hi:[1,0]
	v_pk_mul_f32 v[8:9], v[8:9], v[16:17] op_sel_hi:[1,0]
	v_pk_mul_f32 v[6:7], v[0:1], v[12:13]
	v_pk_mul_f32 v[0:1], v[2:3], v[16:17] op_sel_hi:[1,0]
	v_pk_mul_f32 v[8:9], v[8:9], v[18:19]
	v_pk_mul_f32 v[4:5], v[0:1], v[4:5]
	v_cvt_pk_bf16_f32 v0, v8, v9
	v_cvt_pk_bf16_f32 v3, v4, v5
	v_mad_i64_i32 v[4:5], s[4:5], v64, s57, v[56:57]
	v_cvt_pk_bf16_f32 v1, v10, v11
	v_cvt_pk_bf16_f32 v2, v6, v7
	v_lshl_add_u64 v[4:5], v[4:5], 0, v[142:143]
	global_store_dwordx4 v[4:5], v[0:3], off
	s_branch .LBB0_1363
